# baseline (speedup 1.0000x reference)
; DEVI float silu(float x) { return x * __builtin_amdgcn_rcpf(1.f + __expf(-x)); }
; template <int EPI, int NRM>
; DEVI void epilogue(acc_t& acc, int pn, int trow, const EpiArgs& e, const float* rl, bf16* shmx) {
;   int tid_ = threadIdx.x; asm volatile("" : "+v"(tid_));
;   const int wid = tid_ >> 6, lane = tid_ & 63, wr = wid >> 2, wc = wid & 3, fr = lane & 15, fq = lane >> 4;
;   const int fl0 = wr * 64 + fq * 4;
;   const int tk0 = trow + wc * 32 + fr;
;   float rs[2][2];
;   if constexpr (NRM) {
; #pragma unroll
;     for (int bj = 0; bj < 2; ++bj)
; #pragma unroll
;       for (int n = 0; n < 2; ++n) rs[bj][n] = rl[wc * 32 + fr + bj * 128 + n * 16];
;     ...
;   } else if constexpr (EPI == EPI_SWIGLU) {
; #pragma unroll
;     for (int bj = 0; bj < 2; ++bj)
; #pragma unroll
;       for (int m = 0; m < 4; ++m)
; #pragma unroll
;         for (int n = 0; n < 2; ++n) {
;           float r[4];
; #pragma unroll
;           for (int j = 0; j < 4; ++j) r[j] = silu(acc[0][bj][m][n][j] * rs[bj][n]) * (acc[1][bj][m][n][j] * rs[bj][n]);
;           uint2 o; o.x = pack2(r[0], r[1]); o.y = pack2(r[2], r[3]);
;           const unsigned off = (unsigned)((tk0 + bj * 128 + n * 16) * DFF + pn * 128 + m * 16 + fl0);
;           *reinterpret_cast<uint2*>(e.o0 + off) = o;
;         }
.LBB0_325:
	v_and_b32_e32 v170, 15, v136
	v_bfe_u32 v171, v136, 4, 2
	v_lshrrev_b32_e32 v172, 6, v136
	v_and_b32_e32 v173, 3, v172
	v_lshrrev_b32_e32 v174, 2, v172
	v_lshlrev_b32_e32 v175, 13, v173
	v_lshl_add_u32 v175, v174, 16, v175
	v_add_u32_e32 v175, 0x8000, v175
	v_lshl_add_u32 v176, v170, 7, v175
	v_and_b32_e32 v177, 1, v171
	v_lshl_add_u32 v176, v177, 3, v176
	v_lshrrev_b32_e32 v177, 1, v171
	v_and_b32_e32 v178, 7, v170
	v_add_u32_e32 v179, 0, v177
	v_xor_b32_e32 v179, v179, v178
	v_lshl_add_u32 v164, v179, 4, v176
	v_add_u32_e32 v179, 2, v177
	v_xor_b32_e32 v179, v179, v178
	v_lshl_add_u32 v165, v179, 4, v176
	v_add_u32_e32 v179, 4, v177
	v_xor_b32_e32 v179, v179, v178
	v_lshl_add_u32 v166, v179, 4, v176
	v_add_u32_e32 v179, 6, v177
	v_xor_b32_e32 v179, v179, v178
	v_lshl_add_u32 v167, v179, 4, v176
	v_and_b32_e32 v180, 63, v136
	v_lshl_add_u32 v168, v180, 4, v175
	v_lshrrev_b32_e32 v181, 3, v180
	v_and_b32_e32 v182, 7, v180
	v_xor_b32_e32 v182, v182, v181
	s_lshl_b32 s9, s12, 8
	v_lshl_add_u32 v183, v173, 5, v181
	v_add_u32_e32 v183, s9, v183
	v_mul_u32_u24_e32 v183, 0x1600, v183
	s_lshl_b32 s9, s14, 7
	v_lshl_add_u32 v179, v174, 6, s9
	v_lshl_add_u32 v179, v182, 3, v179
	v_add_lshl_u32 v169, v183, v179, 1
	v_mov_b32_e32 v130, v136
	s_lshl_b32 s11, s16, 10
	s_and_b32 s11, s11, 0x400
	v_and_b32_e32 v141, 15, v130
	v_ashrrev_i32_e32 v142, 2, v130
	v_lshrrev_b32_e32 v143, 2, v130
	v_lshrrev_b32_e32 v130, 1, v130
	s_add_i32 s11, s11, 0
	v_and_b32_e32 v130, 0x60, v130
	s_add_i32 s11, s11, 0x20000
	v_lshlrev_b32_e32 v132, 2, v130
	v_lshlrev_b32_e32 v133, 2, v141
	v_add3_u32 v132, s11, v132, v133
	ds_read2_b32 v[134:135], v132 offset1:16
	ds_read2_b32 v[132:133], v132 offset0:128 offset1:144
	s_lshl_b32 s9, s12, 8
	v_or3_b32 v130, v141, s9, v130
	s_lshl_b32 s9, s14, 7
	v_and_b32_e32 v142, 0xffffffc0, v142
	v_and_or_b32 v141, v143, 12, s9
	s_waitcnt lgkmcnt(1)
	v_pk_mul_f32 v[122:123], v[122:123], v[134:135] op_sel_hi:[1,0]
	v_add_u32_e32 v141, v141, v142
	v_mul_f32_e32 v142, 0xbfb8aa3b, v122
	v_mul_f32_e32 v143, 0xbfb8aa3b, v123
	v_exp_f32_e32 v142, v142
	v_exp_f32_e32 v143, v143
	v_pk_mul_f32 v[126:127], v[126:127], v[134:135] op_sel_hi:[1,0]
	s_movk_i32 s9, 0x1600
	v_add_f32_e32 v142, 1.0, v142
	v_add_f32_e32 v143, 1.0, v143
	v_rcp_f32_e32 v142, v142
	v_rcp_f32_e32 v143, v143
	v_pk_mul_f32 v[106:107], v[106:107], v[134:135] op_sel_hi:[1,0]
	v_pk_mul_f32 v[110:111], v[110:111], v[134:135] op_sel_hi:[1,0]
	v_pk_mul_f32 v[108:109], v[108:109], v[134:135] op_sel_hi:[1,0]
	v_pk_mul_f32 v[122:123], v[122:123], v[142:143]
	v_pk_mul_f32 v[90:91], v[90:91], v[134:135] op_sel_hi:[1,0]
	v_pk_mul_f32 v[122:123], v[126:127], v[122:123]
	v_pk_mul_f32 v[94:95], v[94:95], v[134:135] op_sel_hi:[1,0]
	v_cvt_pk_bf16_f32 v126, v122, v123
	v_pk_mul_f32 v[122:123], v[124:125], v[134:135] op_sel_hi:[1,0]
	v_pk_mul_f32 v[92:93], v[92:93], v[134:135] op_sel_hi:[1,0]
	v_mul_f32_e32 v124, 0xbfb8aa3b, v122
	v_mul_f32_e32 v125, 0xbfb8aa3b, v123
	v_exp_f32_e32 v124, v124
	v_exp_f32_e32 v125, v125
	v_pk_mul_f32 v[74:75], v[74:75], v[134:135] op_sel_hi:[1,0]
	v_pk_mul_f32 v[78:79], v[78:79], v[134:135] op_sel_hi:[1,0]
	v_add_f32_e32 v124, 1.0, v124
	v_add_f32_e32 v125, 1.0, v125
	v_rcp_f32_e32 v124, v124
	v_rcp_f32_e32 v125, v125
	v_pk_mul_f32 v[76:77], v[76:77], v[134:135] op_sel_hi:[1,0]
	s_waitcnt lgkmcnt(0)
	v_pk_mul_f32 v[58:59], v[58:59], v[132:133] op_sel_hi:[1,0]
	v_pk_mul_f32 v[62:63], v[62:63], v[132:133] op_sel_hi:[1,0]
	v_pk_mul_f32 v[122:123], v[122:123], v[124:125]
	v_pk_mul_f32 v[124:125], v[128:129], v[134:135] op_sel_hi:[1,0]
	v_pk_mul_f32 v[42:43], v[42:43], v[132:133] op_sel_hi:[1,0]
	v_pk_mul_f32 v[122:123], v[124:125], v[122:123]
	v_pk_mul_f32 v[46:47], v[46:47], v[132:133] op_sel_hi:[1,0]
	v_cvt_pk_bf16_f32 v127, v122, v123
	v_mul_lo_u32 v123, v130, s9
	v_add_u32_e32 v130, v141, v123
	v_mov_b32_e32 v122, v135
	v_lshl_add_u64 v[124:125], v[130:131], 1, s[2:3]
	v_pk_mul_f32 v[114:115], v[114:115], v[122:123] op_sel_hi:[1,0]
	ds_write_b64 v164, v[126:127]
	v_mul_f32_e32 v124, 0xbfb8aa3b, v114
	v_mul_f32_e32 v125, 0xbfb8aa3b, v115
	v_exp_f32_e32 v124, v124
	v_exp_f32_e32 v125, v125
	v_pk_mul_f32 v[118:119], v[118:119], v[122:123] op_sel_hi:[1,0]
	v_pk_mul_f32 v[98:99], v[98:99], v[122:123] op_sel_hi:[1,0]
	v_add_f32_e32 v124, 1.0, v124
	v_add_f32_e32 v125, 1.0, v125
	v_rcp_f32_e32 v124, v124
	v_rcp_f32_e32 v125, v125
	v_pk_mul_f32 v[102:103], v[102:103], v[122:123] op_sel_hi:[1,0]
	v_pk_mul_f32 v[100:101], v[100:101], v[122:123] op_sel_hi:[1,0]
	v_pk_mul_f32 v[82:83], v[82:83], v[122:123] op_sel_hi:[1,0]
	v_pk_mul_f32 v[114:115], v[114:115], v[124:125]
	v_pk_mul_f32 v[86:87], v[86:87], v[122:123] op_sel_hi:[1,0]
	v_pk_mul_f32 v[114:115], v[118:119], v[114:115]
	v_pk_mul_f32 v[84:85], v[84:85], v[122:123] op_sel_hi:[1,0]
	v_cvt_pk_bf16_f32 v118, v114, v115
	v_pk_mul_f32 v[114:115], v[116:117], v[122:123] op_sel_hi:[1,0]
	v_pk_mul_f32 v[66:67], v[66:67], v[122:123] op_sel_hi:[1,0]
	v_mul_f32_e32 v116, 0xbfb8aa3b, v114
	v_mul_f32_e32 v117, 0xbfb8aa3b, v115
	v_exp_f32_e32 v116, v116
	v_exp_f32_e32 v117, v117
	v_pk_mul_f32 v[70:71], v[70:71], v[122:123] op_sel_hi:[1,0]
	v_pk_mul_f32 v[68:69], v[68:69], v[122:123] op_sel_hi:[1,0]
	v_add_f32_e32 v116, 1.0, v116
	v_add_f32_e32 v117, 1.0, v117
	v_rcp_f32_e32 v116, v116
	v_rcp_f32_e32 v117, v117
	v_pk_mul_f32 v[44:45], v[44:45], v[132:133] op_sel_hi:[1,0]
	v_pk_mul_f32 v[26:27], v[26:27], v[132:133] op_sel_hi:[1,0]
	v_pk_mul_f32 v[30:31], v[30:31], v[132:133] op_sel_hi:[1,0]
	v_pk_mul_f32 v[114:115], v[114:115], v[116:117]
	v_pk_mul_f32 v[116:117], v[120:121], v[122:123] op_sel_hi:[1,0]
; DEVI float silu(float x) { return x * __builtin_amdgcn_rcpf(1.f + __expf(-x)); }
; template <int EPI, int NRM>
; DEVI void epilogue(acc_t& acc, int pn, int trow, const EpiArgs& e, const float* rl, bf16* shmx) {
;     ...
;   } else if constexpr (EPI == EPI_SWIGLU) {
; #pragma unroll
;     for (int bj = 0; bj < 2; ++bj)
; #pragma unroll
;       for (int m = 0; m < 4; ++m)
; #pragma unroll
;         for (int n = 0; n < 2; ++n) {
;           float r[4];
; #pragma unroll
;           for (int j = 0; j < 4; ++j) r[j] = silu(acc[0][bj][m][n][j] * rs[bj][n]) * (acc[1][bj][m][n][j] * rs[bj][n]);
;           uint2 o; o.x = pack2(r[0], r[1]); o.y = pack2(r[2], r[3]);
;           const unsigned off = (unsigned)((tk0 + bj * 128 + n * 16) * DFF + pn * 128 + m * 16 + fl0);
;           *reinterpret_cast<uint2*>(e.o0 + off) = o;
;         }
	v_pk_mul_f32 v[28:29], v[28:29], v[132:133] op_sel_hi:[1,0]
	v_pk_mul_f32 v[114:115], v[116:117], v[114:115]
	v_pk_mul_f32 v[10:11], v[10:11], v[132:133] op_sel_hi:[1,0]
	v_cvt_pk_bf16_f32 v119, v114, v115
	v_add_u32_e32 v115, 0x16000, v123
	v_add_u32_e32 v130, v115, v141
	v_lshl_add_u64 v[116:117], v[130:131], 1, s[2:3]
	ds_write_b64 v164, v[118:119] offset:2048
	v_mul_f32_e32 v116, 0xbfb8aa3b, v106
	v_mul_f32_e32 v117, 0xbfb8aa3b, v107
	v_exp_f32_e32 v116, v116
	v_exp_f32_e32 v117, v117
	v_or_b32_e32 v114, 16, v141
	v_add_u32_e32 v130, v114, v123
	v_add_f32_e32 v116, 1.0, v116
	v_add_f32_e32 v117, 1.0, v117
	v_rcp_f32_e32 v116, v116
	v_rcp_f32_e32 v117, v117
	v_pk_mul_f32 v[14:15], v[14:15], v[132:133] op_sel_hi:[1,0]
	v_pk_mul_f32 v[12:13], v[12:13], v[132:133] op_sel_hi:[1,0]
	s_add_i32 s16, s16, 1
	v_pk_mul_f32 v[106:107], v[106:107], v[116:117]
	s_andn2_b64 vcc, exec, s[4:5]
	v_pk_mul_f32 v[106:107], v[110:111], v[106:107]
	s_mov_b32 s14, s8
	v_cvt_pk_bf16_f32 v106, v106, v107
	v_mul_f32_e32 v107, 0xbfb8aa3b, v108
	v_exp_f32_e32 v107, v107
	s_mov_b32 s12, s10
	v_add_f32_e32 v107, 1.0, v107
	v_rcp_f32_e32 v110, v107
	v_mul_f32_e32 v107, 0xbfb8aa3b, v109
	v_exp_f32_e32 v107, v107
	s_nop 0
	v_add_f32_e32 v107, 1.0, v107
	v_rcp_f32_e32 v111, v107
	s_nop 0
	v_pk_mul_f32 v[108:109], v[108:109], v[110:111]
	v_pk_mul_f32 v[110:111], v[112:113], v[134:135] op_sel_hi:[1,0]
	s_nop 0
	v_pk_mul_f32 v[108:109], v[110:111], v[108:109]
	s_nop 0
	v_cvt_pk_bf16_f32 v107, v108, v109
	v_lshl_add_u64 v[108:109], v[130:131], 1, s[2:3]
	ds_write_b64 v165, v[106:107]
	v_mul_f32_e32 v106, 0xbfb8aa3b, v98
	v_mul_f32_e32 v107, 0xbfb8aa3b, v99
	v_exp_f32_e32 v106, v106
	v_exp_f32_e32 v107, v107
	v_add_u32_e32 v130, v114, v115
	v_add_f32_e32 v106, 1.0, v106
	v_add_f32_e32 v107, 1.0, v107
	v_rcp_f32_e32 v106, v106
	v_rcp_f32_e32 v107, v107
	s_nop 0
	v_pk_mul_f32 v[98:99], v[98:99], v[106:107]
	s_nop 0
	v_pk_mul_f32 v[98:99], v[102:103], v[98:99]
	s_nop 0
	v_cvt_pk_bf16_f32 v98, v98, v99
	v_mul_f32_e32 v99, 0xbfb8aa3b, v100
	v_exp_f32_e32 v99, v99
	s_nop 0
	v_add_f32_e32 v99, 1.0, v99
	v_rcp_f32_e32 v102, v99
	v_mul_f32_e32 v99, 0xbfb8aa3b, v101
	v_exp_f32_e32 v99, v99
	s_nop 0
	v_add_f32_e32 v99, 1.0, v99
	v_rcp_f32_e32 v103, v99
	s_nop 0
	v_pk_mul_f32 v[100:101], v[100:101], v[102:103]
	v_pk_mul_f32 v[102:103], v[104:105], v[122:123] op_sel_hi:[1,0]
	s_nop 0
	v_pk_mul_f32 v[100:101], v[102:103], v[100:101]
	s_nop 0
	v_cvt_pk_bf16_f32 v99, v100, v101
	v_lshl_add_u64 v[100:101], v[130:131], 1, s[2:3]
	ds_write_b64 v165, v[98:99] offset:2048
	v_mul_f32_e32 v99, 0xbfb8aa3b, v90
	v_exp_f32_e32 v99, v99
	v_or_b32_e32 v98, 32, v141
	v_add_u32_e32 v130, v98, v123
	v_add_f32_e32 v99, 1.0, v99
	v_rcp_f32_e32 v100, v99
	v_mul_f32_e32 v99, 0xbfb8aa3b, v91
	v_exp_f32_e32 v99, v99
	s_nop 0
	v_add_f32_e32 v99, 1.0, v99
	v_rcp_f32_e32 v101, v99
	s_nop 0
	v_pk_mul_f32 v[90:91], v[90:91], v[100:101]
	s_nop 0
	v_pk_mul_f32 v[90:91], v[94:95], v[90:91]
	s_nop 0
	v_cvt_pk_bf16_f32 v90, v90, v91
	v_mul_f32_e32 v91, 0xbfb8aa3b, v92
	v_exp_f32_e32 v91, v91
	s_nop 0
	v_add_f32_e32 v91, 1.0, v91
	v_rcp_f32_e32 v94, v91
	v_mul_f32_e32 v91, 0xbfb8aa3b, v93
	v_exp_f32_e32 v91, v91
	s_nop 0
	v_add_f32_e32 v91, 1.0, v91
	v_rcp_f32_e32 v95, v91
	s_nop 0
	v_pk_mul_f32 v[92:93], v[92:93], v[94:95]
	v_pk_mul_f32 v[94:95], v[96:97], v[134:135] op_sel_hi:[1,0]
	s_nop 0
	v_pk_mul_f32 v[92:93], v[94:95], v[92:93]
	s_nop 0
	v_cvt_pk_bf16_f32 v91, v92, v93
	v_lshl_add_u64 v[92:93], v[130:131], 1, s[2:3]
	ds_write_b64 v166, v[90:91]
	v_mul_f32_e32 v90, 0xbfb8aa3b, v82
	v_mul_f32_e32 v91, 0xbfb8aa3b, v83
	v_exp_f32_e32 v90, v90
	v_exp_f32_e32 v91, v91
	v_add_u32_e32 v130, v98, v115
	v_add_f32_e32 v90, 1.0, v90
	v_add_f32_e32 v91, 1.0, v91
	v_rcp_f32_e32 v90, v90
	v_rcp_f32_e32 v91, v91
	s_nop 0
	v_pk_mul_f32 v[82:83], v[82:83], v[90:91]
	s_nop 0
	v_pk_mul_f32 v[82:83], v[86:87], v[82:83]
	s_nop 0
	v_cvt_pk_bf16_f32 v82, v82, v83
	v_mul_f32_e32 v83, 0xbfb8aa3b, v84
	v_exp_f32_e32 v83, v83
	s_nop 0
	v_add_f32_e32 v83, 1.0, v83
	v_rcp_f32_e32 v86, v83
	v_mul_f32_e32 v83, 0xbfb8aa3b, v85
	v_exp_f32_e32 v83, v83
	s_nop 0
	v_add_f32_e32 v83, 1.0, v83
	v_rcp_f32_e32 v87, v83
	s_nop 0
	v_pk_mul_f32 v[84:85], v[84:85], v[86:87]
	v_pk_mul_f32 v[86:87], v[88:89], v[122:123] op_sel_hi:[1,0]
	s_nop 0
	v_pk_mul_f32 v[84:85], v[86:87], v[84:85]
	s_nop 0
	v_cvt_pk_bf16_f32 v83, v84, v85
	v_lshl_add_u64 v[84:85], v[130:131], 1, s[2:3]
	ds_write_b64 v166, v[82:83] offset:2048
	v_mul_f32_e32 v83, 0xbfb8aa3b, v74
	v_exp_f32_e32 v83, v83
	v_or_b32_e32 v82, 48, v141
	v_add_u32_e32 v130, v82, v123
	v_add_f32_e32 v83, 1.0, v83
	v_rcp_f32_e32 v84, v83
	v_mul_f32_e32 v83, 0xbfb8aa3b, v75
	v_exp_f32_e32 v83, v83
	s_nop 0
	v_add_f32_e32 v83, 1.0, v83
	v_rcp_f32_e32 v85, v83
	s_nop 0
	v_pk_mul_f32 v[74:75], v[74:75], v[84:85]
	s_nop 0
	v_pk_mul_f32 v[74:75], v[78:79], v[74:75]
	s_nop 0
	v_cvt_pk_bf16_f32 v74, v74, v75
	v_mul_f32_e32 v75, 0xbfb8aa3b, v76
	v_exp_f32_e32 v75, v75
	s_nop 0
	v_add_f32_e32 v75, 1.0, v75
	v_rcp_f32_e32 v78, v75
	v_mul_f32_e32 v75, 0xbfb8aa3b, v77
	v_exp_f32_e32 v75, v75
	s_nop 0
	v_add_f32_e32 v75, 1.0, v75
	v_rcp_f32_e32 v79, v75
	s_nop 0
	v_pk_mul_f32 v[76:77], v[76:77], v[78:79]
	v_pk_mul_f32 v[78:79], v[80:81], v[134:135] op_sel_hi:[1,0]
	s_nop 0
	v_pk_mul_f32 v[76:77], v[78:79], v[76:77]
	s_nop 0
	v_cvt_pk_bf16_f32 v75, v76, v77
	v_lshl_add_u64 v[76:77], v[130:131], 1, s[2:3]
	ds_write_b64 v167, v[74:75]
	v_mul_f32_e32 v74, 0xbfb8aa3b, v66
	v_mul_f32_e32 v75, 0xbfb8aa3b, v67
	v_exp_f32_e32 v74, v74
	v_exp_f32_e32 v75, v75
	v_add_u32_e32 v130, v82, v115
	v_add_f32_e32 v74, 1.0, v74
	v_add_f32_e32 v75, 1.0, v75
	v_rcp_f32_e32 v74, v74
	v_rcp_f32_e32 v75, v75
	s_nop 0
	v_pk_mul_f32 v[66:67], v[66:67], v[74:75]
	s_nop 0
	v_pk_mul_f32 v[66:67], v[70:71], v[66:67]
	s_nop 0
	v_cvt_pk_bf16_f32 v66, v66, v67
	v_mul_f32_e32 v67, 0xbfb8aa3b, v68
	v_exp_f32_e32 v67, v67
	s_nop 0
	v_add_f32_e32 v67, 1.0, v67
	v_rcp_f32_e32 v70, v67
	v_mul_f32_e32 v67, 0xbfb8aa3b, v69
	v_exp_f32_e32 v67, v67
	s_nop 0
	v_add_f32_e32 v67, 1.0, v67
	v_rcp_f32_e32 v71, v67
	s_nop 0
	v_pk_mul_f32 v[68:69], v[68:69], v[70:71]
	v_pk_mul_f32 v[70:71], v[72:73], v[122:123] op_sel_hi:[1,0]
	s_nop 0
	v_pk_mul_f32 v[68:69], v[70:71], v[68:69]
	s_nop 0
	v_cvt_pk_bf16_f32 v67, v68, v69
	v_lshl_add_u64 v[68:69], v[130:131], 1, s[2:3]
	ds_write_b64 v167, v[66:67] offset:2048
	s_waitcnt lgkmcnt(0)
; DEVI float silu(float x) { return x * __builtin_amdgcn_rcpf(1.f + __expf(-x)); }
; template <int EPI, int NRM>
; DEVI void epilogue(acc_t& acc, int pn, int trow, const EpiArgs& e, const float* rl, bf16* shmx) {
;     ...
;   } else if constexpr (EPI == EPI_SWIGLU) {
; #pragma unroll
;     for (int bj = 0; bj < 2; ++bj)
; #pragma unroll
;       for (int m = 0; m < 4; ++m)
; #pragma unroll
;         for (int n = 0; n < 2; ++n) {
;           float r[4];
; #pragma unroll
;           for (int j = 0; j < 4; ++j) r[j] = silu(acc[0][bj][m][n][j] * rs[bj][n]) * (acc[1][bj][m][n][j] * rs[bj][n]);
;           uint2 o; o.x = pack2(r[0], r[1]); o.y = pack2(r[2], r[3]);
;           const unsigned off = (unsigned)((tk0 + bj * 128 + n * 16) * DFF + pn * 128 + m * 16 + fl0);
;           *reinterpret_cast<uint2*>(e.o0 + off) = o;
;         }
	ds_read_b128 v[172:175], v168
	ds_read_b128 v[176:179], v168 offset:1024
	ds_read_b128 v[180:183], v168 offset:2048
	ds_read_b128 v[184:187], v168 offset:3072
	v_add_u32_e32 v204, 0x16000, v169
	v_add_u32_e32 v205, 0x2c000, v169
	v_add_u32_e32 v206, 0x42000, v169
	s_waitcnt lgkmcnt(3)
	global_store_dwordx4 v169, v[172:175], s[2:3] nt
	s_waitcnt lgkmcnt(2)
	global_store_dwordx4 v204, v[176:179], s[2:3] nt
	s_waitcnt lgkmcnt(1)
	global_store_dwordx4 v205, v[180:183], s[2:3] nt
	s_waitcnt lgkmcnt(0)
	global_store_dwordx4 v206, v[184:187], s[2:3] nt
	v_mul_f32_e32 v66, 0xbfb8aa3b, v58
	v_mul_f32_e32 v67, 0xbfb8aa3b, v59
	v_exp_f32_e32 v66, v66
	v_exp_f32_e32 v67, v67
	v_add_f32_e32 v66, 1.0, v66
	v_add_f32_e32 v67, 1.0, v67
	v_rcp_f32_e32 v66, v66
	v_rcp_f32_e32 v67, v67
	s_nop 0
	v_pk_mul_f32 v[58:59], v[58:59], v[66:67]
	s_nop 0
	v_pk_mul_f32 v[58:59], v[62:63], v[58:59]
	s_nop 0
	v_cvt_pk_bf16_f32 v62, v58, v59
	v_pk_mul_f32 v[58:59], v[60:61], v[132:133] op_sel_hi:[1,0]
	s_nop 0
	v_mul_f32_e32 v60, 0xbfb8aa3b, v58
	v_mul_f32_e32 v61, 0xbfb8aa3b, v59
	v_exp_f32_e32 v60, v60
	v_exp_f32_e32 v61, v61
	v_add_f32_e32 v60, 1.0, v60
	v_add_f32_e32 v61, 1.0, v61
	v_rcp_f32_e32 v60, v60
	v_rcp_f32_e32 v61, v61
	s_nop 0
	v_pk_mul_f32 v[58:59], v[58:59], v[60:61]
	v_pk_mul_f32 v[60:61], v[64:65], v[132:133] op_sel_hi:[1,0]
	s_nop 0
	v_pk_mul_f32 v[58:59], v[60:61], v[58:59]
	s_nop 0
	v_cvt_pk_bf16_f32 v63, v58, v59
	v_add_u32_e32 v59, 0xb0000, v123
	v_add_u32_e32 v130, v59, v141
	v_mov_b32_e32 v58, v133
	v_lshl_add_u64 v[60:61], v[130:131], 1, s[2:3]
	v_pk_mul_f32 v[50:51], v[50:51], v[58:59] op_sel_hi:[1,0]
	ds_write_b64 v164, v[62:63] offset:4096
	v_mul_f32_e32 v60, 0xbfb8aa3b, v50
	v_mul_f32_e32 v61, 0xbfb8aa3b, v51
	v_exp_f32_e32 v60, v60
	v_exp_f32_e32 v61, v61
	v_pk_mul_f32 v[54:55], v[54:55], v[58:59] op_sel_hi:[1,0]
	v_pk_mul_f32 v[34:35], v[34:35], v[58:59] op_sel_hi:[1,0]
	v_add_f32_e32 v60, 1.0, v60
	v_add_f32_e32 v61, 1.0, v61
	v_rcp_f32_e32 v60, v60
	v_rcp_f32_e32 v61, v61
	v_pk_mul_f32 v[38:39], v[38:39], v[58:59] op_sel_hi:[1,0]
	v_pk_mul_f32 v[36:37], v[36:37], v[58:59] op_sel_hi:[1,0]
	v_pk_mul_f32 v[18:19], v[18:19], v[58:59] op_sel_hi:[1,0]
	v_pk_mul_f32 v[50:51], v[50:51], v[60:61]
	v_pk_mul_f32 v[22:23], v[22:23], v[58:59] op_sel_hi:[1,0]
	v_pk_mul_f32 v[50:51], v[54:55], v[50:51]
	v_pk_mul_f32 v[20:21], v[20:21], v[58:59] op_sel_hi:[1,0]
	v_cvt_pk_bf16_f32 v54, v50, v51
	v_pk_mul_f32 v[50:51], v[52:53], v[58:59] op_sel_hi:[1,0]
	v_pk_mul_f32 v[2:3], v[2:3], v[58:59] op_sel_hi:[1,0]
	v_mul_f32_e32 v52, 0xbfb8aa3b, v50
	v_mul_f32_e32 v53, 0xbfb8aa3b, v51
	v_exp_f32_e32 v52, v52
	v_exp_f32_e32 v53, v53
	v_pk_mul_f32 v[6:7], v[6:7], v[58:59] op_sel_hi:[1,0]
	v_pk_mul_f32 v[4:5], v[4:5], v[58:59] op_sel_hi:[1,0]
	v_add_f32_e32 v52, 1.0, v52
	v_add_f32_e32 v53, 1.0, v53
	v_rcp_f32_e32 v52, v52
	v_rcp_f32_e32 v53, v53
	s_nop 0
	v_pk_mul_f32 v[50:51], v[50:51], v[52:53]
	v_pk_mul_f32 v[52:53], v[56:57], v[58:59] op_sel_hi:[1,0]
	s_nop 0
	v_pk_mul_f32 v[50:51], v[52:53], v[50:51]
	s_nop 0
	v_cvt_pk_bf16_f32 v55, v50, v51
	v_mul_f32_e32 v51, 0xbfb8aa3b, v42
	v_exp_f32_e32 v51, v51
	v_add_u32_e32 v50, 0xc6000, v123
	v_add_u32_e32 v130, v50, v141
	v_lshl_add_u64 v[52:53], v[130:131], 1, s[2:3]
	v_add_f32_e32 v51, 1.0, v51
	ds_write_b64 v164, v[54:55] offset:6144
	v_rcp_f32_e32 v52, v51
	v_mul_f32_e32 v51, 0xbfb8aa3b, v43
	v_exp_f32_e32 v51, v51
	v_add_u32_e32 v130, v114, v59
	v_add_f32_e32 v51, 1.0, v51
	v_rcp_f32_e32 v53, v51
	s_nop 0
	v_pk_mul_f32 v[42:43], v[42:43], v[52:53]
	s_nop 0
	v_pk_mul_f32 v[42:43], v[46:47], v[42:43]
	s_nop 0
	v_cvt_pk_bf16_f32 v42, v42, v43
	v_mul_f32_e32 v43, 0xbfb8aa3b, v44
	v_exp_f32_e32 v43, v43
	s_nop 0
	v_add_f32_e32 v43, 1.0, v43
	v_rcp_f32_e32 v46, v43
	v_mul_f32_e32 v43, 0xbfb8aa3b, v45
	v_exp_f32_e32 v43, v43
	s_nop 0
	v_add_f32_e32 v43, 1.0, v43
	v_rcp_f32_e32 v47, v43
	s_nop 0
	v_pk_mul_f32 v[44:45], v[44:45], v[46:47]
	v_pk_mul_f32 v[46:47], v[48:49], v[132:133] op_sel_hi:[1,0]
	s_nop 0
	v_pk_mul_f32 v[44:45], v[46:47], v[44:45]
	s_nop 0
	v_cvt_pk_bf16_f32 v43, v44, v45
	v_lshl_add_u64 v[44:45], v[130:131], 1, s[2:3]
	ds_write_b64 v165, v[42:43] offset:4096
	v_mul_f32_e32 v42, 0xbfb8aa3b, v34
	v_mul_f32_e32 v43, 0xbfb8aa3b, v35
	v_exp_f32_e32 v42, v42
	v_exp_f32_e32 v43, v43
	v_add_u32_e32 v130, v114, v50
	v_add_f32_e32 v42, 1.0, v42
	v_add_f32_e32 v43, 1.0, v43
	v_rcp_f32_e32 v42, v42
	v_rcp_f32_e32 v43, v43
	s_nop 0
	v_pk_mul_f32 v[34:35], v[34:35], v[42:43]
	s_nop 0
	v_pk_mul_f32 v[34:35], v[38:39], v[34:35]
	s_nop 0
	v_cvt_pk_bf16_f32 v34, v34, v35
	v_mul_f32_e32 v35, 0xbfb8aa3b, v36
	v_exp_f32_e32 v35, v35
	s_nop 0
	v_add_f32_e32 v35, 1.0, v35
	v_rcp_f32_e32 v38, v35
	v_mul_f32_e32 v35, 0xbfb8aa3b, v37
; DEVI float silu(float x) { return x * __builtin_amdgcn_rcpf(1.f + __expf(-x)); }
; template <int EPI, int NRM>
; DEVI void epilogue(acc_t& acc, int pn, int trow, const EpiArgs& e, const float* rl, bf16* shmx) {
;     ...
;   } else if constexpr (EPI == EPI_SWIGLU) {
; #pragma unroll
;     for (int bj = 0; bj < 2; ++bj)
; #pragma unroll
;       for (int m = 0; m < 4; ++m)
; #pragma unroll
;         for (int n = 0; n < 2; ++n) {
;           float r[4];
; #pragma unroll
;           for (int j = 0; j < 4; ++j) r[j] = silu(acc[0][bj][m][n][j] * rs[bj][n]) * (acc[1][bj][m][n][j] * rs[bj][n]);
;           uint2 o; o.x = pack2(r[0], r[1]); o.y = pack2(r[2], r[3]);
;           const unsigned off = (unsigned)((tk0 + bj * 128 + n * 16) * DFF + pn * 128 + m * 16 + fl0);
;           *reinterpret_cast<uint2*>(e.o0 + off) = o;
;         }
	v_exp_f32_e32 v35, v35
	s_nop 0
	v_add_f32_e32 v35, 1.0, v35
	v_rcp_f32_e32 v39, v35
	s_nop 0
	v_pk_mul_f32 v[36:37], v[36:37], v[38:39]
	v_pk_mul_f32 v[38:39], v[40:41], v[58:59] op_sel_hi:[1,0]
	s_nop 0
	v_pk_mul_f32 v[36:37], v[38:39], v[36:37]
	s_nop 0
	v_cvt_pk_bf16_f32 v35, v36, v37
	v_lshl_add_u64 v[36:37], v[130:131], 1, s[2:3]
	ds_write_b64 v165, v[34:35] offset:6144
	v_mul_f32_e32 v34, 0xbfb8aa3b, v26
	v_mul_f32_e32 v35, 0xbfb8aa3b, v27
	v_exp_f32_e32 v34, v34
	v_exp_f32_e32 v35, v35
	v_add_u32_e32 v130, v98, v59
	v_add_f32_e32 v34, 1.0, v34
	v_add_f32_e32 v35, 1.0, v35
	v_rcp_f32_e32 v34, v34
	v_rcp_f32_e32 v35, v35
	s_nop 0
	v_pk_mul_f32 v[26:27], v[26:27], v[34:35]
	s_nop 0
	v_pk_mul_f32 v[26:27], v[30:31], v[26:27]
	s_nop 0
	v_cvt_pk_bf16_f32 v26, v26, v27
	v_mul_f32_e32 v27, 0xbfb8aa3b, v28
	v_exp_f32_e32 v27, v27
	s_nop 0
	v_add_f32_e32 v27, 1.0, v27
	v_rcp_f32_e32 v30, v27
	v_mul_f32_e32 v27, 0xbfb8aa3b, v29
	v_exp_f32_e32 v27, v27
	s_nop 0
	v_add_f32_e32 v27, 1.0, v27
	v_rcp_f32_e32 v31, v27
	s_nop 0
	v_pk_mul_f32 v[28:29], v[28:29], v[30:31]
	v_pk_mul_f32 v[30:31], v[32:33], v[132:133] op_sel_hi:[1,0]
	s_nop 0
	v_pk_mul_f32 v[28:29], v[30:31], v[28:29]
	s_nop 0
	v_cvt_pk_bf16_f32 v27, v28, v29
	v_lshl_add_u64 v[28:29], v[130:131], 1, s[2:3]
	ds_write_b64 v166, v[26:27] offset:4096
	v_mul_f32_e32 v26, 0xbfb8aa3b, v18
	v_mul_f32_e32 v27, 0xbfb8aa3b, v19
	v_exp_f32_e32 v26, v26
	v_exp_f32_e32 v27, v27
	v_add_u32_e32 v130, v98, v50
	v_add_f32_e32 v26, 1.0, v26
	v_add_f32_e32 v27, 1.0, v27
	v_rcp_f32_e32 v26, v26
	v_rcp_f32_e32 v27, v27
	s_nop 0
	v_pk_mul_f32 v[18:19], v[18:19], v[26:27]
	s_nop 0
	v_pk_mul_f32 v[18:19], v[22:23], v[18:19]
	s_nop 0
	v_cvt_pk_bf16_f32 v18, v18, v19
	v_mul_f32_e32 v19, 0xbfb8aa3b, v20
	v_exp_f32_e32 v19, v19
	s_nop 0
	v_add_f32_e32 v19, 1.0, v19
	v_rcp_f32_e32 v22, v19
	v_mul_f32_e32 v19, 0xbfb8aa3b, v21
	v_exp_f32_e32 v19, v19
	s_nop 0
	v_add_f32_e32 v19, 1.0, v19
	v_rcp_f32_e32 v23, v19
	s_nop 0
	v_pk_mul_f32 v[20:21], v[20:21], v[22:23]
	v_pk_mul_f32 v[22:23], v[24:25], v[58:59] op_sel_hi:[1,0]
	s_nop 0
	v_pk_mul_f32 v[20:21], v[22:23], v[20:21]
	s_nop 0
	v_cvt_pk_bf16_f32 v19, v20, v21
	v_lshl_add_u64 v[20:21], v[130:131], 1, s[2:3]
	ds_write_b64 v166, v[18:19] offset:6144
	v_mul_f32_e32 v18, 0xbfb8aa3b, v10
	v_mul_f32_e32 v19, 0xbfb8aa3b, v11
	v_exp_f32_e32 v18, v18
	v_exp_f32_e32 v19, v19
	v_add_u32_e32 v130, v82, v59
	v_add_f32_e32 v18, 1.0, v18
	v_add_f32_e32 v19, 1.0, v19
	v_rcp_f32_e32 v18, v18
	v_rcp_f32_e32 v19, v19
	s_nop 0
	v_pk_mul_f32 v[10:11], v[10:11], v[18:19]
	s_nop 0
	v_pk_mul_f32 v[10:11], v[14:15], v[10:11]
	s_nop 0
	v_cvt_pk_bf16_f32 v10, v10, v11
	v_mul_f32_e32 v11, 0xbfb8aa3b, v12
	v_exp_f32_e32 v11, v11
	s_nop 0
	v_add_f32_e32 v11, 1.0, v11
	v_rcp_f32_e32 v14, v11
	v_mul_f32_e32 v11, 0xbfb8aa3b, v13
	v_exp_f32_e32 v11, v11
	s_nop 0
	v_add_f32_e32 v11, 1.0, v11
	v_rcp_f32_e32 v15, v11
	s_nop 0
	v_pk_mul_f32 v[12:13], v[12:13], v[14:15]
	v_pk_mul_f32 v[14:15], v[16:17], v[132:133] op_sel_hi:[1,0]
	s_nop 0
	v_pk_mul_f32 v[12:13], v[14:15], v[12:13]
	s_nop 0
	v_cvt_pk_bf16_f32 v11, v12, v13
	v_lshl_add_u64 v[12:13], v[130:131], 1, s[2:3]
	ds_write_b64 v167, v[10:11] offset:4096
	v_mul_f32_e32 v10, 0xbfb8aa3b, v2
	v_mul_f32_e32 v11, 0xbfb8aa3b, v3
	v_exp_f32_e32 v10, v10
	v_exp_f32_e32 v11, v11
	v_add_u32_e32 v130, v82, v50
	v_add_f32_e32 v10, 1.0, v10
	v_add_f32_e32 v11, 1.0, v11
	v_rcp_f32_e32 v10, v10
	v_rcp_f32_e32 v11, v11
	s_nop 0
	v_pk_mul_f32 v[2:3], v[2:3], v[10:11]
	s_nop 0
	v_pk_mul_f32 v[2:3], v[6:7], v[2:3]
	s_nop 0
	v_cvt_pk_bf16_f32 v2, v2, v3
	v_mul_f32_e32 v3, 0xbfb8aa3b, v4
	v_exp_f32_e32 v3, v3
	s_nop 0
	v_add_f32_e32 v3, 1.0, v3
	v_rcp_f32_e32 v6, v3
	v_mul_f32_e32 v3, 0xbfb8aa3b, v5
	v_exp_f32_e32 v3, v3
	s_nop 0
	v_add_f32_e32 v3, 1.0, v3
	v_rcp_f32_e32 v7, v3
	s_nop 0
	v_pk_mul_f32 v[4:5], v[4:5], v[6:7]
	v_pk_mul_f32 v[6:7], v[8:9], v[58:59] op_sel_hi:[1,0]
	s_nop 0
	v_pk_mul_f32 v[4:5], v[6:7], v[4:5]
	s_nop 0
	v_cvt_pk_bf16_f32 v3, v4, v5
	v_lshl_add_u64 v[4:5], v[130:131], 1, s[2:3]
	ds_write_b64 v167, v[2:3] offset:6144
	s_waitcnt lgkmcnt(0)
	ds_read_b128 v[188:191], v168 offset:4096
	ds_read_b128 v[192:195], v168 offset:5120
	ds_read_b128 v[196:199], v168 offset:6144
	ds_read_b128 v[200:203], v168 offset:7168
	v_add_u32_e32 v207, 0x160000, v169
	v_add_u32_e32 v208, 0x176000, v169
	v_add_u32_e32 v209, 0x18c000, v169
	v_add_u32_e32 v210, 0x1a2000, v169
	s_waitcnt lgkmcnt(3)
	global_store_dwordx4 v207, v[188:191], s[2:3] nt
	s_waitcnt lgkmcnt(2)
	global_store_dwordx4 v208, v[192:195], s[2:3] nt
	s_waitcnt lgkmcnt(1)
	global_store_dwordx4 v209, v[196:199], s[2:3] nt
	s_waitcnt lgkmcnt(0)
	global_store_dwordx4 v210, v[200:203], s[2:3] nt
	s_cbranch_vccz .LBB0_338

; DEVI float silu(float x) { return x * __builtin_amdgcn_rcpf(1.f + __expf(-x)); }
; template <int EPI, int NRM>
; DEVI void epilogue(acc_t& acc, int pn, int trow, const EpiArgs& e, const float* rl, bf16* shmx) {
;     ...
;   } else if constexpr (EPI == EPI_SWIGLU) {
; #pragma unroll
;     for (int bj = 0; bj < 2; ++bj)
; #pragma unroll
;       for (int m = 0; m < 4; ++m)
; #pragma unroll
;         for (int n = 0; n < 2; ++n) {
;           float r[4];
; #pragma unroll
;           for (int j = 0; j < 4; ++j) r[j] = silu(acc[0][bj][m][n][j] * rs[bj][n]) * (acc[1][bj][m][n][j] * rs[bj][n]);
;           uint2 o; o.x = pack2(r[0], r[1]); o.y = pack2(r[2], r[3]);
;           const unsigned off = (unsigned)((tk0 + bj * 128 + n * 16) * DFF + pn * 128 + m * 16 + fl0);
;           *reinterpret_cast<uint2*>(e.o0 + off) = o;
;         }
.LBB0_1224:
	v_and_b32_e32 v170, 15, v136
	v_bfe_u32 v171, v136, 4, 2
	v_lshrrev_b32_e32 v172, 6, v136
	v_and_b32_e32 v173, 3, v172
	v_lshrrev_b32_e32 v174, 2, v172
	v_lshlrev_b32_e32 v175, 13, v173
	v_lshl_add_u32 v175, v174, 16, v175
	v_add_u32_e32 v175, 0x8000, v175
	v_lshl_add_u32 v176, v170, 7, v175
	v_and_b32_e32 v177, 1, v171
	v_lshl_add_u32 v176, v177, 3, v176
	v_lshrrev_b32_e32 v177, 1, v171
	v_and_b32_e32 v178, 7, v170
	v_add_u32_e32 v179, 0, v177
	v_xor_b32_e32 v179, v179, v178
	v_lshl_add_u32 v164, v179, 4, v176
	v_add_u32_e32 v179, 2, v177
	v_xor_b32_e32 v179, v179, v178
	v_lshl_add_u32 v165, v179, 4, v176
	v_add_u32_e32 v179, 4, v177
	v_xor_b32_e32 v179, v179, v178
	v_lshl_add_u32 v166, v179, 4, v176
	v_add_u32_e32 v179, 6, v177
	v_xor_b32_e32 v179, v179, v178
	v_lshl_add_u32 v167, v179, 4, v176
	v_and_b32_e32 v180, 63, v136
	v_lshl_add_u32 v168, v180, 4, v175
	v_lshrrev_b32_e32 v181, 3, v180
	v_and_b32_e32 v182, 7, v180
	v_xor_b32_e32 v182, v182, v181
	s_lshl_b32 s9, s12, 8
	v_lshl_add_u32 v183, v173, 5, v181
	v_add_u32_e32 v183, s9, v183
	v_mul_u32_u24_e32 v183, 0x1600, v183
	s_lshl_b32 s9, s14, 7
	v_lshl_add_u32 v179, v174, 6, s9
	v_lshl_add_u32 v179, v182, 3, v179
	v_add_lshl_u32 v169, v183, v179, 1
	v_mov_b32_e32 v130, v136
	s_lshl_b32 s11, s16, 10
	s_and_b32 s11, s11, 0x400
	v_and_b32_e32 v141, 15, v130
	v_ashrrev_i32_e32 v142, 2, v130
	v_lshrrev_b32_e32 v143, 2, v130
	v_lshrrev_b32_e32 v130, 1, v130
	s_add_i32 s11, s11, 0
	v_and_b32_e32 v130, 0x60, v130
	s_add_i32 s11, s11, 0x20000
	v_lshlrev_b32_e32 v132, 2, v130
	v_lshlrev_b32_e32 v133, 2, v141
	v_add3_u32 v132, s11, v132, v133
	ds_read2_b32 v[134:135], v132 offset1:16
	ds_read2_b32 v[132:133], v132 offset0:128 offset1:144
	s_lshl_b32 s9, s12, 8
	v_or3_b32 v130, v141, s9, v130
	s_lshl_b32 s9, s14, 7
	s_waitcnt lgkmcnt(1)
	v_pk_mul_f32 v[122:123], v[122:123], v[134:135] op_sel_hi:[1,0]
	v_and_or_b32 v141, v143, 12, s9
	v_mul_f32_e32 v143, 0xbfb8aa3b, v122
	v_mul_f32_e32 v144, 0xbfb8aa3b, v123
	v_exp_f32_e32 v143, v143
	v_exp_f32_e32 v144, v144
	v_and_b32_e32 v142, 0xffffffc0, v142
	v_pk_mul_f32 v[124:125], v[124:125], v[134:135] op_sel_hi:[1,0]
	v_add_u32_e32 v141, v141, v142
	v_add_f32_e32 v142, 1.0, v143
	v_add_f32_e32 v143, 1.0, v144
	v_mul_f32_e32 v144, 0xbfb8aa3b, v124
	v_mul_f32_e32 v145, 0xbfb8aa3b, v125
	v_rcp_f32_e32 v142, v142
	v_rcp_f32_e32 v143, v143
	v_exp_f32_e32 v144, v144
	v_exp_f32_e32 v145, v145
	v_pk_mul_f32 v[126:127], v[126:127], v[134:135] op_sel_hi:[1,0]
	v_pk_mul_f32 v[122:123], v[122:123], v[142:143]
	v_add_f32_e32 v142, 1.0, v144
	v_add_f32_e32 v143, 1.0, v145
	v_rcp_f32_e32 v142, v142
	v_rcp_f32_e32 v143, v143
	v_pk_mul_f32 v[122:123], v[126:127], v[122:123]
	v_pk_mul_f32 v[106:107], v[106:107], v[134:135] op_sel_hi:[1,0]
	v_cvt_pk_bf16_f32 v126, v122, v123
	v_pk_mul_f32 v[122:123], v[124:125], v[142:143]
	v_pk_mul_f32 v[124:125], v[128:129], v[134:135] op_sel_hi:[1,0]
	v_pk_mul_f32 v[108:109], v[108:109], v[134:135] op_sel_hi:[1,0]
	v_pk_mul_f32 v[122:123], v[124:125], v[122:123]
	v_pk_mul_f32 v[110:111], v[110:111], v[134:135] op_sel_hi:[1,0]
	v_cvt_pk_bf16_f32 v127, v122, v123
	v_mul_lo_u32 v123, v130, s41
	v_mov_b32_e32 v122, v135
	v_pk_mul_f32 v[114:115], v[114:115], v[122:123] op_sel_hi:[1,0]
	v_add_u32_e32 v130, v141, v123
	v_mul_f32_e32 v128, 0xbfb8aa3b, v114
	v_mul_f32_e32 v129, 0xbfb8aa3b, v115
	v_exp_f32_e32 v128, v128
	v_exp_f32_e32 v129, v129
	v_lshl_add_u64 v[124:125], v[130:131], 1, s[2:3]
	v_pk_mul_f32 v[116:117], v[116:117], v[122:123] op_sel_hi:[1,0]
	ds_write_b64 v164, v[126:127]
	v_add_f32_e32 v124, 1.0, v128
	v_add_f32_e32 v125, 1.0, v129
	v_mul_f32_e32 v126, 0xbfb8aa3b, v116
	v_mul_f32_e32 v127, 0xbfb8aa3b, v117
	v_rcp_f32_e32 v124, v124
	v_rcp_f32_e32 v125, v125
	v_exp_f32_e32 v126, v126
	v_exp_f32_e32 v127, v127
	v_pk_mul_f32 v[118:119], v[118:119], v[122:123] op_sel_hi:[1,0]
	v_pk_mul_f32 v[114:115], v[114:115], v[124:125]
	v_add_f32_e32 v124, 1.0, v126
	v_add_f32_e32 v125, 1.0, v127
	v_rcp_f32_e32 v124, v124
	v_rcp_f32_e32 v125, v125
	v_pk_mul_f32 v[114:115], v[118:119], v[114:115]
	v_pk_mul_f32 v[118:119], v[120:121], v[122:123] op_sel_hi:[1,0]
	v_cvt_pk_bf16_f32 v114, v114, v115
	v_pk_mul_f32 v[116:117], v[116:117], v[124:125]
	v_pk_mul_f32 v[98:99], v[98:99], v[122:123] op_sel_hi:[1,0]
	v_pk_mul_f32 v[116:117], v[118:119], v[116:117]
	v_add_u32_e32 v118, 0x16000, v123
	v_add_u32_e32 v130, v118, v141
	v_cvt_pk_bf16_f32 v115, v116, v117
	v_lshl_add_u64 v[116:117], v[130:131], 1, s[2:3]
	ds_write_b64 v164, v[114:115] offset:2048
	v_mul_f32_e32 v114, 0xbfb8aa3b, v106
	v_mul_f32_e32 v115, 0xbfb8aa3b, v107
	v_exp_f32_e32 v114, v114
	v_exp_f32_e32 v115, v115
	v_mul_f32_e32 v117, 0xbfb8aa3b, v108
	v_mul_f32_e32 v119, 0xbfb8aa3b, v109
	v_add_f32_e32 v114, 1.0, v114
	v_add_f32_e32 v115, 1.0, v115
	v_rcp_f32_e32 v114, v114
	v_rcp_f32_e32 v115, v115
	v_exp_f32_e32 v117, v117
	v_exp_f32_e32 v119, v119
	v_or_b32_e32 v116, 16, v141
	v_pk_mul_f32 v[106:107], v[106:107], v[114:115]
	v_add_f32_e32 v114, 1.0, v117
	v_add_f32_e32 v115, 1.0, v119
	v_rcp_f32_e32 v114, v114
	v_rcp_f32_e32 v115, v115
	v_pk_mul_f32 v[106:107], v[110:111], v[106:107]
	v_pk_mul_f32 v[110:111], v[112:113], v[134:135] op_sel_hi:[1,0]
	v_add_u32_e32 v130, v116, v123
	v_pk_mul_f32 v[108:109], v[108:109], v[114:115]
	v_cvt_pk_bf16_f32 v106, v106, v107
	v_pk_mul_f32 v[108:109], v[110:111], v[108:109]
	v_mul_f32_e32 v110, 0xbfb8aa3b, v98
	v_mul_f32_e32 v111, 0xbfb8aa3b, v99
	v_exp_f32_e32 v110, v110
	v_exp_f32_e32 v111, v111
	v_cvt_pk_bf16_f32 v107, v108, v109
	v_lshl_add_u64 v[108:109], v[130:131], 1, s[2:3]
	v_pk_mul_f32 v[100:101], v[100:101], v[122:123] op_sel_hi:[1,0]
; DEVI float silu(float x) { return x * __builtin_amdgcn_rcpf(1.f + __expf(-x)); }
; template <int EPI, int NRM>
; DEVI void epilogue(acc_t& acc, int pn, int trow, const EpiArgs& e, const float* rl, bf16* shmx) {
;     ...
;   } else if constexpr (EPI == EPI_SWIGLU) {
; #pragma unroll
;     for (int bj = 0; bj < 2; ++bj)
; #pragma unroll
;       for (int m = 0; m < 4; ++m)
; #pragma unroll
;         for (int n = 0; n < 2; ++n) {
;           float r[4];
; #pragma unroll
;           for (int j = 0; j < 4; ++j) r[j] = silu(acc[0][bj][m][n][j] * rs[bj][n]) * (acc[1][bj][m][n][j] * rs[bj][n]);
;           uint2 o; o.x = pack2(r[0], r[1]); o.y = pack2(r[2], r[3]);
;           const unsigned off = (unsigned)((tk0 + bj * 128 + n * 16) * DFF + pn * 128 + m * 16 + fl0);
;           *reinterpret_cast<uint2*>(e.o0 + off) = o;
;         }
	ds_write_b64 v165, v[106:107]
	v_add_f32_e32 v106, 1.0, v110
	v_add_f32_e32 v107, 1.0, v111
	v_mul_f32_e32 v108, 0xbfb8aa3b, v100
	v_mul_f32_e32 v109, 0xbfb8aa3b, v101
	v_rcp_f32_e32 v106, v106
	v_rcp_f32_e32 v107, v107
	v_exp_f32_e32 v108, v108
	v_exp_f32_e32 v109, v109
	v_pk_mul_f32 v[102:103], v[102:103], v[122:123] op_sel_hi:[1,0]
	v_pk_mul_f32 v[98:99], v[98:99], v[106:107]
	v_add_f32_e32 v106, 1.0, v108
	v_add_f32_e32 v107, 1.0, v109
	v_rcp_f32_e32 v106, v106
	v_rcp_f32_e32 v107, v107
	v_pk_mul_f32 v[98:99], v[102:103], v[98:99]
	v_pk_mul_f32 v[102:103], v[104:105], v[122:123] op_sel_hi:[1,0]
	v_add_u32_e32 v130, v116, v118
	v_pk_mul_f32 v[100:101], v[100:101], v[106:107]
	v_cvt_pk_bf16_f32 v98, v98, v99
	v_pk_mul_f32 v[100:101], v[102:103], v[100:101]
	v_pk_mul_f32 v[90:91], v[90:91], v[134:135] op_sel_hi:[1,0]
	v_cvt_pk_bf16_f32 v99, v100, v101
	v_lshl_add_u64 v[100:101], v[130:131], 1, s[2:3]
	ds_write_b64 v165, v[98:99] offset:2048
	v_mul_f32_e32 v98, 0xbfb8aa3b, v90
	v_mul_f32_e32 v99, 0xbfb8aa3b, v91
	v_exp_f32_e32 v98, v98
	v_exp_f32_e32 v99, v99
	v_pk_mul_f32 v[92:93], v[92:93], v[134:135] op_sel_hi:[1,0]
	v_pk_mul_f32 v[94:95], v[94:95], v[134:135] op_sel_hi:[1,0]
	v_add_f32_e32 v98, 1.0, v98
	v_add_f32_e32 v99, 1.0, v99
	v_mul_f32_e32 v101, 0xbfb8aa3b, v92
	v_mul_f32_e32 v102, 0xbfb8aa3b, v93
	v_rcp_f32_e32 v98, v98
	v_rcp_f32_e32 v99, v99
	v_exp_f32_e32 v101, v101
	v_exp_f32_e32 v102, v102
	v_pk_mul_f32 v[82:83], v[82:83], v[122:123] op_sel_hi:[1,0]
	v_pk_mul_f32 v[90:91], v[90:91], v[98:99]
	v_add_f32_e32 v98, 1.0, v101
	v_add_f32_e32 v99, 1.0, v102
	v_rcp_f32_e32 v98, v98
	v_rcp_f32_e32 v99, v99
	v_pk_mul_f32 v[90:91], v[94:95], v[90:91]
	v_pk_mul_f32 v[94:95], v[96:97], v[134:135] op_sel_hi:[1,0]
	v_or_b32_e32 v100, 32, v141
	v_pk_mul_f32 v[92:93], v[92:93], v[98:99]
	v_add_u32_e32 v130, v100, v123
	v_pk_mul_f32 v[92:93], v[94:95], v[92:93]
	v_mul_f32_e32 v94, 0xbfb8aa3b, v82
	v_mul_f32_e32 v95, 0xbfb8aa3b, v83
	v_exp_f32_e32 v94, v94
	v_exp_f32_e32 v95, v95
	v_cvt_pk_bf16_f32 v90, v90, v91
	v_cvt_pk_bf16_f32 v91, v92, v93
	v_lshl_add_u64 v[92:93], v[130:131], 1, s[2:3]
	v_pk_mul_f32 v[84:85], v[84:85], v[122:123] op_sel_hi:[1,0]
	ds_write_b64 v166, v[90:91]
	v_add_f32_e32 v90, 1.0, v94
	v_add_f32_e32 v91, 1.0, v95
	v_mul_f32_e32 v92, 0xbfb8aa3b, v84
	v_mul_f32_e32 v93, 0xbfb8aa3b, v85
	v_rcp_f32_e32 v90, v90
	v_rcp_f32_e32 v91, v91
	v_exp_f32_e32 v92, v92
	v_exp_f32_e32 v93, v93
	v_pk_mul_f32 v[86:87], v[86:87], v[122:123] op_sel_hi:[1,0]
	v_pk_mul_f32 v[82:83], v[82:83], v[90:91]
	v_add_f32_e32 v90, 1.0, v92
	v_add_f32_e32 v91, 1.0, v93
	v_rcp_f32_e32 v90, v90
	v_rcp_f32_e32 v91, v91
	v_pk_mul_f32 v[82:83], v[86:87], v[82:83]
	v_pk_mul_f32 v[86:87], v[88:89], v[122:123] op_sel_hi:[1,0]
	v_add_u32_e32 v130, v100, v118
	v_pk_mul_f32 v[84:85], v[84:85], v[90:91]
	v_cvt_pk_bf16_f32 v82, v82, v83
	v_pk_mul_f32 v[84:85], v[86:87], v[84:85]
	v_pk_mul_f32 v[74:75], v[74:75], v[134:135] op_sel_hi:[1,0]
	v_cvt_pk_bf16_f32 v83, v84, v85
	v_lshl_add_u64 v[84:85], v[130:131], 1, s[2:3]
	ds_write_b64 v166, v[82:83] offset:2048
	v_mul_f32_e32 v82, 0xbfb8aa3b, v74
	v_mul_f32_e32 v83, 0xbfb8aa3b, v75
	v_exp_f32_e32 v82, v82
	v_exp_f32_e32 v83, v83
	v_pk_mul_f32 v[76:77], v[76:77], v[134:135] op_sel_hi:[1,0]
	v_pk_mul_f32 v[78:79], v[78:79], v[134:135] op_sel_hi:[1,0]
	v_add_f32_e32 v82, 1.0, v82
	v_add_f32_e32 v83, 1.0, v83
	v_mul_f32_e32 v85, 0xbfb8aa3b, v76
	v_mul_f32_e32 v86, 0xbfb8aa3b, v77
	v_rcp_f32_e32 v82, v82
	v_rcp_f32_e32 v83, v83
	v_exp_f32_e32 v85, v85
	v_exp_f32_e32 v86, v86
	v_pk_mul_f32 v[66:67], v[66:67], v[122:123] op_sel_hi:[1,0]
	v_pk_mul_f32 v[74:75], v[74:75], v[82:83]
	v_add_f32_e32 v82, 1.0, v85
	v_add_f32_e32 v83, 1.0, v86
	v_rcp_f32_e32 v82, v82
	v_rcp_f32_e32 v83, v83
	v_pk_mul_f32 v[74:75], v[78:79], v[74:75]
	v_pk_mul_f32 v[78:79], v[80:81], v[134:135] op_sel_hi:[1,0]
	v_or_b32_e32 v84, 48, v141
	v_pk_mul_f32 v[76:77], v[76:77], v[82:83]
	v_add_u32_e32 v130, v84, v123
	v_pk_mul_f32 v[76:77], v[78:79], v[76:77]
	v_mul_f32_e32 v78, 0xbfb8aa3b, v66
	v_mul_f32_e32 v79, 0xbfb8aa3b, v67
	v_exp_f32_e32 v78, v78
	v_exp_f32_e32 v79, v79
	v_cvt_pk_bf16_f32 v74, v74, v75
	v_cvt_pk_bf16_f32 v75, v76, v77
	v_lshl_add_u64 v[76:77], v[130:131], 1, s[2:3]
	v_pk_mul_f32 v[68:69], v[68:69], v[122:123] op_sel_hi:[1,0]
	ds_write_b64 v167, v[74:75]
	v_add_f32_e32 v74, 1.0, v78
	v_add_f32_e32 v75, 1.0, v79
	v_mul_f32_e32 v76, 0xbfb8aa3b, v68
	v_mul_f32_e32 v77, 0xbfb8aa3b, v69
	v_rcp_f32_e32 v74, v74
	v_rcp_f32_e32 v75, v75
	v_exp_f32_e32 v76, v76
	v_exp_f32_e32 v77, v77
	v_pk_mul_f32 v[70:71], v[70:71], v[122:123] op_sel_hi:[1,0]
	v_pk_mul_f32 v[66:67], v[66:67], v[74:75]
	v_add_f32_e32 v74, 1.0, v76
	v_add_f32_e32 v75, 1.0, v77
	v_rcp_f32_e32 v74, v74
	v_rcp_f32_e32 v75, v75
	v_pk_mul_f32 v[66:67], v[70:71], v[66:67]
	v_pk_mul_f32 v[70:71], v[72:73], v[122:123] op_sel_hi:[1,0]
	s_waitcnt lgkmcnt(0)
	v_pk_mul_f32 v[58:59], v[58:59], v[132:133] op_sel_hi:[1,0]
	v_pk_mul_f32 v[68:69], v[68:69], v[74:75]
	v_add_u32_e32 v130, v84, v118
	v_pk_mul_f32 v[68:69], v[70:71], v[68:69]
	v_mul_f32_e32 v70, 0xbfb8aa3b, v58
	v_mul_f32_e32 v71, 0xbfb8aa3b, v59
	v_exp_f32_e32 v70, v70
	v_exp_f32_e32 v71, v71
	v_cvt_pk_bf16_f32 v66, v66, v67
	v_cvt_pk_bf16_f32 v67, v68, v69
	v_lshl_add_u64 v[68:69], v[130:131], 1, s[2:3]
	v_pk_mul_f32 v[60:61], v[60:61], v[132:133] op_sel_hi:[1,0]
	ds_write_b64 v167, v[66:67] offset:2048
	s_waitcnt lgkmcnt(0)
	ds_read_b128 v[172:175], v168
	ds_read_b128 v[176:179], v168 offset:1024
	ds_read_b128 v[180:183], v168 offset:2048
	ds_read_b128 v[184:187], v168 offset:3072
	v_add_u32_e32 v204, 0x16000, v169
	v_add_u32_e32 v205, 0x2c000, v169
	v_add_u32_e32 v206, 0x42000, v169
	s_waitcnt lgkmcnt(3)
; DEVI float silu(float x) { return x * __builtin_amdgcn_rcpf(1.f + __expf(-x)); }
; template <int EPI, int NRM>
; DEVI void epilogue(acc_t& acc, int pn, int trow, const EpiArgs& e, const float* rl, bf16* shmx) {
;     ...
;           float r[4];
; #pragma unroll
;           for (int j = 0; j < 4; ++j) r[j] = silu(acc[0][bj][m][n][j] * rs[bj][n]) * (acc[1][bj][m][n][j] * rs[bj][n]);
;           uint2 o; o.x = pack2(r[0], r[1]); o.y = pack2(r[2], r[3]);
;           const unsigned off = (unsigned)((tk0 + bj * 128 + n * 16) * DFF + pn * 128 + m * 16 + fl0);
;           *reinterpret_cast<uint2*>(e.o0 + off) = o;
	global_store_dwordx4 v169, v[172:175], s[2:3] nt
	s_waitcnt lgkmcnt(2)
	global_store_dwordx4 v204, v[176:179], s[2:3] nt
	s_waitcnt lgkmcnt(1)
	global_store_dwordx4 v205, v[180:183], s[2:3] nt
	s_waitcnt lgkmcnt(0)
	global_store_dwordx4 v206, v[184:187], s[2:3] nt
	v_add_f32_e32 v66, 1.0, v70
	v_add_f32_e32 v67, 1.0, v71
	v_mul_f32_e32 v68, 0xbfb8aa3b, v60
	v_mul_f32_e32 v69, 0xbfb8aa3b, v61
	v_rcp_f32_e32 v66, v66
	v_rcp_f32_e32 v67, v67
	v_exp_f32_e32 v68, v68
	v_exp_f32_e32 v69, v69
	v_pk_mul_f32 v[62:63], v[62:63], v[132:133] op_sel_hi:[1,0]
	v_pk_mul_f32 v[58:59], v[58:59], v[66:67]
	v_add_f32_e32 v66, 1.0, v68
	v_add_f32_e32 v67, 1.0, v69
	v_rcp_f32_e32 v66, v66
	v_rcp_f32_e32 v67, v67
	v_pk_mul_f32 v[58:59], v[62:63], v[58:59]
	v_pk_mul_f32 v[42:43], v[42:43], v[132:133] op_sel_hi:[1,0]
	v_cvt_pk_bf16_f32 v62, v58, v59
	v_pk_mul_f32 v[58:59], v[60:61], v[66:67]
	v_pk_mul_f32 v[60:61], v[64:65], v[132:133] op_sel_hi:[1,0]
	v_pk_mul_f32 v[44:45], v[44:45], v[132:133] op_sel_hi:[1,0]
	v_pk_mul_f32 v[58:59], v[60:61], v[58:59]
	v_pk_mul_f32 v[46:47], v[46:47], v[132:133] op_sel_hi:[1,0]
	v_cvt_pk_bf16_f32 v63, v58, v59
	v_add_u32_e32 v59, 0xb0000, v123
	v_mov_b32_e32 v58, v133
	v_pk_mul_f32 v[50:51], v[50:51], v[58:59] op_sel_hi:[1,0]
	v_add_u32_e32 v130, v59, v141
	v_mul_f32_e32 v64, 0xbfb8aa3b, v50
	v_mul_f32_e32 v65, 0xbfb8aa3b, v51
	v_exp_f32_e32 v64, v64
	v_exp_f32_e32 v65, v65
	v_lshl_add_u64 v[60:61], v[130:131], 1, s[2:3]
	v_pk_mul_f32 v[52:53], v[52:53], v[58:59] op_sel_hi:[1,0]
	ds_write_b64 v164, v[62:63] offset:4096
	v_add_f32_e32 v60, 1.0, v64
	v_add_f32_e32 v61, 1.0, v65
	v_mul_f32_e32 v62, 0xbfb8aa3b, v52
	v_mul_f32_e32 v63, 0xbfb8aa3b, v53
	v_rcp_f32_e32 v60, v60
	v_rcp_f32_e32 v61, v61
	v_exp_f32_e32 v62, v62
	v_exp_f32_e32 v63, v63
	v_pk_mul_f32 v[54:55], v[54:55], v[58:59] op_sel_hi:[1,0]
	v_pk_mul_f32 v[50:51], v[50:51], v[60:61]
	v_add_f32_e32 v60, 1.0, v62
	v_add_f32_e32 v61, 1.0, v63
	v_rcp_f32_e32 v60, v60
	v_rcp_f32_e32 v61, v61
	v_pk_mul_f32 v[50:51], v[54:55], v[50:51]
	v_pk_mul_f32 v[54:55], v[56:57], v[58:59] op_sel_hi:[1,0]
	v_mul_f32_e32 v56, 0xbfb8aa3b, v43
	v_pk_mul_f32 v[52:53], v[52:53], v[60:61]
	v_exp_f32_e32 v56, v56
	v_pk_mul_f32 v[52:53], v[54:55], v[52:53]
	v_mul_f32_e32 v55, 0xbfb8aa3b, v42
	v_exp_f32_e32 v55, v55
	v_add_u32_e32 v54, 0xc6000, v123
	v_add_u32_e32 v130, v54, v141
	v_cvt_pk_bf16_f32 v50, v50, v51
	v_cvt_pk_bf16_f32 v51, v52, v53
	v_lshl_add_u64 v[52:53], v[130:131], 1, s[2:3]
	ds_write_b64 v164, v[50:51] offset:6144
	v_add_f32_e32 v50, 1.0, v55
	v_add_f32_e32 v51, 1.0, v56
	v_mul_f32_e32 v52, 0xbfb8aa3b, v44
	v_mul_f32_e32 v53, 0xbfb8aa3b, v45
	v_rcp_f32_e32 v50, v50
	v_rcp_f32_e32 v51, v51
	v_exp_f32_e32 v52, v52
	v_exp_f32_e32 v53, v53
	v_pk_mul_f32 v[34:35], v[34:35], v[58:59] op_sel_hi:[1,0]
	v_pk_mul_f32 v[42:43], v[42:43], v[50:51]
	v_add_f32_e32 v50, 1.0, v52
	v_add_f32_e32 v51, 1.0, v53
	v_rcp_f32_e32 v50, v50
	v_rcp_f32_e32 v51, v51
	v_pk_mul_f32 v[42:43], v[46:47], v[42:43]
	v_pk_mul_f32 v[46:47], v[48:49], v[132:133] op_sel_hi:[1,0]
	v_add_u32_e32 v130, v116, v59
	v_pk_mul_f32 v[44:45], v[44:45], v[50:51]
	v_cvt_pk_bf16_f32 v42, v42, v43
	v_pk_mul_f32 v[44:45], v[46:47], v[44:45]
	v_mul_f32_e32 v46, 0xbfb8aa3b, v34
	v_mul_f32_e32 v47, 0xbfb8aa3b, v35
	v_exp_f32_e32 v46, v46
	v_exp_f32_e32 v47, v47
	v_cvt_pk_bf16_f32 v43, v44, v45
	v_lshl_add_u64 v[44:45], v[130:131], 1, s[2:3]
	v_pk_mul_f32 v[36:37], v[36:37], v[58:59] op_sel_hi:[1,0]
	ds_write_b64 v165, v[42:43] offset:4096
	v_add_f32_e32 v42, 1.0, v46
	v_add_f32_e32 v43, 1.0, v47
	v_mul_f32_e32 v44, 0xbfb8aa3b, v36
	v_mul_f32_e32 v45, 0xbfb8aa3b, v37
	v_rcp_f32_e32 v42, v42
	v_rcp_f32_e32 v43, v43
	v_exp_f32_e32 v44, v44
	v_exp_f32_e32 v45, v45
	v_pk_mul_f32 v[38:39], v[38:39], v[58:59] op_sel_hi:[1,0]
	v_pk_mul_f32 v[34:35], v[34:35], v[42:43]
	v_add_f32_e32 v42, 1.0, v44
	v_add_f32_e32 v43, 1.0, v45
	v_rcp_f32_e32 v42, v42
	v_rcp_f32_e32 v43, v43
	v_pk_mul_f32 v[34:35], v[38:39], v[34:35]
	v_pk_mul_f32 v[38:39], v[40:41], v[58:59] op_sel_hi:[1,0]
	v_pk_mul_f32 v[26:27], v[26:27], v[132:133] op_sel_hi:[1,0]
	v_pk_mul_f32 v[36:37], v[36:37], v[42:43]
	v_add_u32_e32 v130, v116, v54
	v_pk_mul_f32 v[36:37], v[38:39], v[36:37]
	v_mul_f32_e32 v38, 0xbfb8aa3b, v26
	v_mul_f32_e32 v39, 0xbfb8aa3b, v27
	v_exp_f32_e32 v38, v38
	v_exp_f32_e32 v39, v39
	v_cvt_pk_bf16_f32 v34, v34, v35
	v_cvt_pk_bf16_f32 v35, v36, v37
	v_lshl_add_u64 v[36:37], v[130:131], 1, s[2:3]
	v_pk_mul_f32 v[28:29], v[28:29], v[132:133] op_sel_hi:[1,0]
	ds_write_b64 v165, v[34:35] offset:6144
	v_add_f32_e32 v34, 1.0, v38
	v_add_f32_e32 v35, 1.0, v39
; DEVI float silu(float x) { return x * __builtin_amdgcn_rcpf(1.f + __expf(-x)); }
; template <int EPI, int NRM>
; DEVI void epilogue(acc_t& acc, int pn, int trow, const EpiArgs& e, const float* rl, bf16* shmx) {
;     ...
;   } else if constexpr (EPI == EPI_SWIGLU) {
; #pragma unroll
;     for (int bj = 0; bj < 2; ++bj)
; #pragma unroll
;       for (int m = 0; m < 4; ++m)
; #pragma unroll
;         for (int n = 0; n < 2; ++n) {
;           float r[4];
; #pragma unroll
;           for (int j = 0; j < 4; ++j) r[j] = silu(acc[0][bj][m][n][j] * rs[bj][n]) * (acc[1][bj][m][n][j] * rs[bj][n]);
;           uint2 o; o.x = pack2(r[0], r[1]); o.y = pack2(r[2], r[3]);
;           const unsigned off = (unsigned)((tk0 + bj * 128 + n * 16) * DFF + pn * 128 + m * 16 + fl0);
;           *reinterpret_cast<uint2*>(e.o0 + off) = o;
;         }
	v_mul_f32_e32 v36, 0xbfb8aa3b, v28
	v_mul_f32_e32 v37, 0xbfb8aa3b, v29
	v_rcp_f32_e32 v34, v34
	v_rcp_f32_e32 v35, v35
	v_exp_f32_e32 v36, v36
	v_exp_f32_e32 v37, v37
	v_pk_mul_f32 v[30:31], v[30:31], v[132:133] op_sel_hi:[1,0]
	v_pk_mul_f32 v[26:27], v[26:27], v[34:35]
	v_add_f32_e32 v34, 1.0, v36
	v_add_f32_e32 v35, 1.0, v37
	v_rcp_f32_e32 v34, v34
	v_rcp_f32_e32 v35, v35
	v_pk_mul_f32 v[26:27], v[30:31], v[26:27]
	v_pk_mul_f32 v[30:31], v[32:33], v[132:133] op_sel_hi:[1,0]
	v_pk_mul_f32 v[18:19], v[18:19], v[58:59] op_sel_hi:[1,0]
	v_pk_mul_f32 v[28:29], v[28:29], v[34:35]
	v_add_u32_e32 v130, v100, v59
	v_pk_mul_f32 v[28:29], v[30:31], v[28:29]
	v_mul_f32_e32 v30, 0xbfb8aa3b, v18
	v_mul_f32_e32 v31, 0xbfb8aa3b, v19
	v_exp_f32_e32 v30, v30
	v_exp_f32_e32 v31, v31
	v_cvt_pk_bf16_f32 v26, v26, v27
	v_cvt_pk_bf16_f32 v27, v28, v29
	v_lshl_add_u64 v[28:29], v[130:131], 1, s[2:3]
	v_pk_mul_f32 v[20:21], v[20:21], v[58:59] op_sel_hi:[1,0]
	ds_write_b64 v166, v[26:27] offset:4096
	v_add_f32_e32 v26, 1.0, v30
	v_add_f32_e32 v27, 1.0, v31
	v_mul_f32_e32 v28, 0xbfb8aa3b, v20
	v_mul_f32_e32 v29, 0xbfb8aa3b, v21
	v_rcp_f32_e32 v26, v26
	v_rcp_f32_e32 v27, v27
	v_exp_f32_e32 v28, v28
	v_exp_f32_e32 v29, v29
	v_pk_mul_f32 v[22:23], v[22:23], v[58:59] op_sel_hi:[1,0]
	v_pk_mul_f32 v[18:19], v[18:19], v[26:27]
	v_add_f32_e32 v26, 1.0, v28
	v_add_f32_e32 v27, 1.0, v29
	v_rcp_f32_e32 v26, v26
	v_rcp_f32_e32 v27, v27
	v_pk_mul_f32 v[18:19], v[22:23], v[18:19]
	v_pk_mul_f32 v[22:23], v[24:25], v[58:59] op_sel_hi:[1,0]
	v_pk_mul_f32 v[10:11], v[10:11], v[132:133] op_sel_hi:[1,0]
	v_pk_mul_f32 v[20:21], v[20:21], v[26:27]
	v_add_u32_e32 v130, v100, v54
	v_pk_mul_f32 v[20:21], v[22:23], v[20:21]
	v_mul_f32_e32 v22, 0xbfb8aa3b, v10
	v_mul_f32_e32 v23, 0xbfb8aa3b, v11
	v_exp_f32_e32 v22, v22
	v_exp_f32_e32 v23, v23
	v_cvt_pk_bf16_f32 v18, v18, v19
	v_cvt_pk_bf16_f32 v19, v20, v21
	v_lshl_add_u64 v[20:21], v[130:131], 1, s[2:3]
	v_pk_mul_f32 v[12:13], v[12:13], v[132:133] op_sel_hi:[1,0]
	ds_write_b64 v166, v[18:19] offset:6144
	v_add_f32_e32 v18, 1.0, v22
	v_add_f32_e32 v19, 1.0, v23
	v_mul_f32_e32 v20, 0xbfb8aa3b, v12
	v_mul_f32_e32 v21, 0xbfb8aa3b, v13
	v_rcp_f32_e32 v18, v18
	v_rcp_f32_e32 v19, v19
	v_exp_f32_e32 v20, v20
	v_exp_f32_e32 v21, v21
	v_pk_mul_f32 v[14:15], v[14:15], v[132:133] op_sel_hi:[1,0]
	v_pk_mul_f32 v[10:11], v[10:11], v[18:19]
	v_add_f32_e32 v18, 1.0, v20
	v_add_f32_e32 v19, 1.0, v21
	v_rcp_f32_e32 v18, v18
	v_rcp_f32_e32 v19, v19
	v_pk_mul_f32 v[10:11], v[14:15], v[10:11]
	v_pk_mul_f32 v[14:15], v[16:17], v[132:133] op_sel_hi:[1,0]
	v_pk_mul_f32 v[2:3], v[2:3], v[58:59] op_sel_hi:[1,0]
	v_pk_mul_f32 v[12:13], v[12:13], v[18:19]
	v_add_u32_e32 v130, v84, v59
	v_pk_mul_f32 v[12:13], v[14:15], v[12:13]
	v_mul_f32_e32 v14, 0xbfb8aa3b, v2
	v_mul_f32_e32 v15, 0xbfb8aa3b, v3
	v_exp_f32_e32 v14, v14
	v_exp_f32_e32 v15, v15
	v_cvt_pk_bf16_f32 v10, v10, v11
	v_cvt_pk_bf16_f32 v11, v12, v13
	v_lshl_add_u64 v[12:13], v[130:131], 1, s[2:3]
	v_pk_mul_f32 v[4:5], v[4:5], v[58:59] op_sel_hi:[1,0]
	ds_write_b64 v167, v[10:11] offset:4096
	v_add_f32_e32 v10, 1.0, v14
	v_add_f32_e32 v11, 1.0, v15
	v_mul_f32_e32 v12, 0xbfb8aa3b, v4
	v_mul_f32_e32 v13, 0xbfb8aa3b, v5
	v_rcp_f32_e32 v10, v10
	v_rcp_f32_e32 v11, v11
	v_exp_f32_e32 v12, v12
	v_exp_f32_e32 v13, v13
	v_pk_mul_f32 v[6:7], v[6:7], v[58:59] op_sel_hi:[1,0]
	v_pk_mul_f32 v[2:3], v[2:3], v[10:11]
	v_add_f32_e32 v10, 1.0, v12
	v_add_f32_e32 v11, 1.0, v13
	v_rcp_f32_e32 v10, v10
	v_rcp_f32_e32 v11, v11
	v_pk_mul_f32 v[2:3], v[6:7], v[2:3]
	v_pk_mul_f32 v[6:7], v[8:9], v[58:59] op_sel_hi:[1,0]
	v_add_u32_e32 v130, v84, v54
	v_pk_mul_f32 v[4:5], v[4:5], v[10:11]
	v_cvt_pk_bf16_f32 v2, v2, v3
	v_pk_mul_f32 v[4:5], v[6:7], v[4:5]
	s_add_i32 s16, s16, 1
	v_cvt_pk_bf16_f32 v3, v4, v5
	v_lshl_add_u64 v[4:5], v[130:131], 1, s[2:3]
	s_andn2_b64 vcc, exec, s[4:5]
	s_mov_b32 s14, s8
	s_mov_b32 s12, s10
	ds_write_b64 v167, v[2:3] offset:6144
	s_waitcnt lgkmcnt(0)
	ds_read_b128 v[188:191], v168 offset:4096
	ds_read_b128 v[192:195], v168 offset:5120
	ds_read_b128 v[196:199], v168 offset:6144
	ds_read_b128 v[200:203], v168 offset:7168
	v_add_u32_e32 v207, 0x160000, v169
	v_add_u32_e32 v208, 0x176000, v169
	v_add_u32_e32 v209, 0x18c000, v169
	v_add_u32_e32 v210, 0x1a2000, v169
	s_waitcnt lgkmcnt(3)
	global_store_dwordx4 v207, v[188:191], s[2:3] nt
	s_waitcnt lgkmcnt(2)
	global_store_dwordx4 v208, v[192:195], s[2:3] nt
	s_waitcnt lgkmcnt(1)
	global_store_dwordx4 v209, v[196:199], s[2:3] nt
	s_waitcnt lgkmcnt(0)
	global_store_dwordx4 v210, v[200:203], s[2:3] nt
	s_cbranch_vccz .LBB0_1237

; DEVI float silu(float x) { return x * __builtin_amdgcn_rcpf(1.f + __expf(-x)); }
; template <int EPI, int NRM>
; DEVI void epilogue(acc_t& acc, int pn, int trow, const EpiArgs& e, const float* rl, bf16* shmx) {
;     ...
;   const int fl0 = wr * 64 + fq * 4;
;   const int tk0 = trow + wc * 32 + fr;
;   float rs[2][2];
;   if constexpr (NRM) {
; #pragma unroll
;     for (int bj = 0; bj < 2; ++bj)
; #pragma unroll
;       for (int n = 0; n < 2; ++n) rs[bj][n] = rl[wc * 32 + fr + bj * 128 + n * 16];
;     ...
;   } else if constexpr (EPI == EPI_SWIGLU) {
; #pragma unroll
;     for (int bj = 0; bj < 2; ++bj)
; #pragma unroll
;       for (int m = 0; m < 4; ++m)
; #pragma unroll
;         for (int n = 0; n < 2; ++n) {
;           float r[4];
; #pragma unroll
;           for (int j = 0; j < 4; ++j) r[j] = silu(acc[0][bj][m][n][j] * rs[bj][n]) * (acc[1][bj][m][n][j] * rs[bj][n]);
;           uint2 o; o.x = pack2(r[0], r[1]); o.y = pack2(r[2], r[3]);
;           const unsigned off = (unsigned)((tk0 + bj * 128 + n * 16) * DFF + pn * 128 + m * 16 + fl0);
;           *reinterpret_cast<uint2*>(e.o0 + off) = o;
;         }
.LBB0_1655:
	v_and_b32_e32 v170, 15, v131
	v_bfe_u32 v171, v131, 4, 2
	v_lshrrev_b32_e32 v172, 6, v131
	v_and_b32_e32 v173, 3, v172
	v_lshrrev_b32_e32 v174, 2, v172
	v_lshlrev_b32_e32 v175, 13, v173
	v_lshl_add_u32 v175, v174, 16, v175
	v_add_u32_e32 v175, 0x8000, v175
	v_lshl_add_u32 v176, v170, 7, v175
	v_and_b32_e32 v177, 1, v171
	v_lshl_add_u32 v176, v177, 3, v176
	v_lshrrev_b32_e32 v177, 1, v171
	v_and_b32_e32 v178, 7, v170
	v_add_u32_e32 v179, 0, v177
	v_xor_b32_e32 v179, v179, v178
	v_lshl_add_u32 v164, v179, 4, v176
	v_add_u32_e32 v179, 2, v177
	v_xor_b32_e32 v179, v179, v178
	v_lshl_add_u32 v165, v179, 4, v176
	v_add_u32_e32 v179, 4, v177
	v_xor_b32_e32 v179, v179, v178
	v_lshl_add_u32 v166, v179, 4, v176
	v_add_u32_e32 v179, 6, v177
	v_xor_b32_e32 v179, v179, v178
	v_lshl_add_u32 v167, v179, 4, v176
	v_and_b32_e32 v180, 63, v131
	v_lshl_add_u32 v168, v180, 4, v175
	v_lshrrev_b32_e32 v181, 3, v180
	v_and_b32_e32 v182, 7, v180
	v_xor_b32_e32 v182, v182, v181
	s_lshl_b32 s9, s12, 8
	v_lshl_add_u32 v183, v173, 5, v181
	v_add_u32_e32 v183, s9, v183
	v_mul_u32_u24_e32 v183, 0x1600, v183
	s_lshl_b32 s9, s14, 7
	v_lshl_add_u32 v179, v174, 6, s9
	v_lshl_add_u32 v179, v182, 3, v179
	v_add_lshl_u32 v169, v183, v179, 1
	v_mov_b32_e32 v132, v131
	s_lshl_b32 s11, s16, 10
	s_and_b32 s11, s11, 0x400
	v_and_b32_e32 v142, 15, v132
	v_ashrrev_i32_e32 v143, 2, v132
	v_lshrrev_b32_e32 v144, 2, v132
	v_lshrrev_b32_e32 v132, 1, v132
	s_add_i32 s11, s11, 0
	v_and_b32_e32 v132, 0x60, v132
	s_add_i32 s11, s11, 0x20000
	v_lshlrev_b32_e32 v134, 2, v132
	v_lshlrev_b32_e32 v135, 2, v142
	v_add3_u32 v134, s11, v134, v135
	ds_read2_b32 v[136:137], v134 offset1:16
	ds_read2_b32 v[134:135], v134 offset0:128 offset1:144
	s_lshl_b32 s9, s12, 8
	v_or3_b32 v132, v142, s9, v132
	s_lshl_b32 s9, s14, 7
	s_waitcnt lgkmcnt(1)
	v_pk_mul_f32 v[122:123], v[122:123], v[136:137] op_sel_hi:[1,0]
	v_and_or_b32 v142, v144, 12, s9
	v_mul_f32_e32 v144, 0xbfb8aa3b, v122
	v_mul_f32_e32 v145, 0xbfb8aa3b, v123
	v_exp_f32_e32 v144, v144
	v_exp_f32_e32 v145, v145
	v_and_b32_e32 v143, 0xffffffc0, v143
	v_pk_mul_f32 v[124:125], v[124:125], v[136:137] op_sel_hi:[1,0]
	v_add_u32_e32 v146, v142, v143
	v_add_f32_e32 v142, 1.0, v144
	v_add_f32_e32 v143, 1.0, v145
	v_mul_f32_e32 v144, 0xbfb8aa3b, v124
	v_mul_f32_e32 v145, 0xbfb8aa3b, v125
	v_rcp_f32_e32 v142, v142
	v_rcp_f32_e32 v143, v143
	v_exp_f32_e32 v144, v144
	v_exp_f32_e32 v145, v145
	v_pk_mul_f32 v[126:127], v[126:127], v[136:137] op_sel_hi:[1,0]
	v_pk_mul_f32 v[122:123], v[122:123], v[142:143]
	v_add_f32_e32 v142, 1.0, v144
	v_add_f32_e32 v143, 1.0, v145
	v_rcp_f32_e32 v142, v142
	v_rcp_f32_e32 v143, v143
	v_pk_mul_f32 v[122:123], v[126:127], v[122:123]
	v_pk_mul_f32 v[106:107], v[106:107], v[136:137] op_sel_hi:[1,0]
	v_cvt_pk_bf16_f32 v126, v122, v123
	v_pk_mul_f32 v[122:123], v[124:125], v[142:143]
	v_pk_mul_f32 v[124:125], v[128:129], v[136:137] op_sel_hi:[1,0]
	v_pk_mul_f32 v[108:109], v[108:109], v[136:137] op_sel_hi:[1,0]
	v_pk_mul_f32 v[122:123], v[124:125], v[122:123]
	v_pk_mul_f32 v[110:111], v[110:111], v[136:137] op_sel_hi:[1,0]
	v_cvt_pk_bf16_f32 v127, v122, v123
	v_mul_lo_u32 v123, v132, s41
	v_mov_b32_e32 v122, v137
	v_pk_mul_f32 v[114:115], v[114:115], v[122:123] op_sel_hi:[1,0]
	v_add_u32_e32 v132, v146, v123
	v_mul_f32_e32 v128, 0xbfb8aa3b, v114
	v_mul_f32_e32 v129, 0xbfb8aa3b, v115
	v_exp_f32_e32 v128, v128
	v_exp_f32_e32 v129, v129
	v_lshl_add_u64 v[124:125], v[132:133], 1, s[2:3]
	v_pk_mul_f32 v[116:117], v[116:117], v[122:123] op_sel_hi:[1,0]
	ds_write_b64 v164, v[126:127]
	v_add_f32_e32 v124, 1.0, v128
	v_add_f32_e32 v125, 1.0, v129
	v_mul_f32_e32 v126, 0xbfb8aa3b, v116
	v_mul_f32_e32 v127, 0xbfb8aa3b, v117
	v_rcp_f32_e32 v124, v124
	v_rcp_f32_e32 v125, v125
	v_exp_f32_e32 v126, v126
	v_exp_f32_e32 v127, v127
	v_pk_mul_f32 v[118:119], v[118:119], v[122:123] op_sel_hi:[1,0]
	v_pk_mul_f32 v[114:115], v[114:115], v[124:125]
	v_add_f32_e32 v124, 1.0, v126
	v_add_f32_e32 v125, 1.0, v127
	v_rcp_f32_e32 v124, v124
	v_rcp_f32_e32 v125, v125
	v_pk_mul_f32 v[114:115], v[118:119], v[114:115]
	v_pk_mul_f32 v[118:119], v[120:121], v[122:123] op_sel_hi:[1,0]
	v_cvt_pk_bf16_f32 v114, v114, v115
	v_pk_mul_f32 v[116:117], v[116:117], v[124:125]
	v_pk_mul_f32 v[98:99], v[98:99], v[122:123] op_sel_hi:[1,0]
	v_pk_mul_f32 v[116:117], v[118:119], v[116:117]
	v_add_u32_e32 v118, 0x16000, v123
	v_add_u32_e32 v132, v118, v146
	v_cvt_pk_bf16_f32 v115, v116, v117
	v_lshl_add_u64 v[116:117], v[132:133], 1, s[2:3]
	ds_write_b64 v164, v[114:115] offset:2048
	v_mul_f32_e32 v114, 0xbfb8aa3b, v106
	v_mul_f32_e32 v115, 0xbfb8aa3b, v107
	v_exp_f32_e32 v114, v114
	v_exp_f32_e32 v115, v115
	v_mul_f32_e32 v117, 0xbfb8aa3b, v108
	v_mul_f32_e32 v119, 0xbfb8aa3b, v109
	v_add_f32_e32 v114, 1.0, v114
	v_add_f32_e32 v115, 1.0, v115
	v_rcp_f32_e32 v114, v114
	v_rcp_f32_e32 v115, v115
	v_exp_f32_e32 v117, v117
	v_exp_f32_e32 v119, v119
	v_or_b32_e32 v116, 16, v146
	v_pk_mul_f32 v[106:107], v[106:107], v[114:115]
	v_add_f32_e32 v114, 1.0, v117
	v_add_f32_e32 v115, 1.0, v119
	v_rcp_f32_e32 v114, v114
	v_rcp_f32_e32 v115, v115
	v_pk_mul_f32 v[106:107], v[110:111], v[106:107]
	v_pk_mul_f32 v[110:111], v[112:113], v[136:137] op_sel_hi:[1,0]
	v_add_u32_e32 v132, v116, v123
	v_pk_mul_f32 v[108:109], v[108:109], v[114:115]
	v_cvt_pk_bf16_f32 v106, v106, v107
	v_pk_mul_f32 v[108:109], v[110:111], v[108:109]
	v_mul_f32_e32 v110, 0xbfb8aa3b, v98
	v_mul_f32_e32 v111, 0xbfb8aa3b, v99
	v_exp_f32_e32 v110, v110
	v_exp_f32_e32 v111, v111
	v_cvt_pk_bf16_f32 v107, v108, v109
	v_lshl_add_u64 v[108:109], v[132:133], 1, s[2:3]
	v_pk_mul_f32 v[100:101], v[100:101], v[122:123] op_sel_hi:[1,0]
; DEVI float silu(float x) { return x * __builtin_amdgcn_rcpf(1.f + __expf(-x)); }
; template <int EPI, int NRM>
; DEVI void epilogue(acc_t& acc, int pn, int trow, const EpiArgs& e, const float* rl, bf16* shmx) {
;     ...
;   } else if constexpr (EPI == EPI_SWIGLU) {
; #pragma unroll
;     for (int bj = 0; bj < 2; ++bj)
; #pragma unroll
;       for (int m = 0; m < 4; ++m)
; #pragma unroll
;         for (int n = 0; n < 2; ++n) {
;           float r[4];
; #pragma unroll
;           for (int j = 0; j < 4; ++j) r[j] = silu(acc[0][bj][m][n][j] * rs[bj][n]) * (acc[1][bj][m][n][j] * rs[bj][n]);
;           uint2 o; o.x = pack2(r[0], r[1]); o.y = pack2(r[2], r[3]);
;           const unsigned off = (unsigned)((tk0 + bj * 128 + n * 16) * DFF + pn * 128 + m * 16 + fl0);
;           *reinterpret_cast<uint2*>(e.o0 + off) = o;
;         }
	ds_write_b64 v165, v[106:107]
	v_add_f32_e32 v106, 1.0, v110
	v_add_f32_e32 v107, 1.0, v111
	v_mul_f32_e32 v108, 0xbfb8aa3b, v100
	v_mul_f32_e32 v109, 0xbfb8aa3b, v101
	v_rcp_f32_e32 v106, v106
	v_rcp_f32_e32 v107, v107
	v_exp_f32_e32 v108, v108
	v_exp_f32_e32 v109, v109
	v_pk_mul_f32 v[102:103], v[102:103], v[122:123] op_sel_hi:[1,0]
	v_pk_mul_f32 v[98:99], v[98:99], v[106:107]
	v_add_f32_e32 v106, 1.0, v108
	v_add_f32_e32 v107, 1.0, v109
	v_rcp_f32_e32 v106, v106
	v_rcp_f32_e32 v107, v107
	v_pk_mul_f32 v[98:99], v[102:103], v[98:99]
	v_pk_mul_f32 v[102:103], v[104:105], v[122:123] op_sel_hi:[1,0]
	v_add_u32_e32 v132, v116, v118
	v_pk_mul_f32 v[100:101], v[100:101], v[106:107]
	v_cvt_pk_bf16_f32 v98, v98, v99
	v_pk_mul_f32 v[100:101], v[102:103], v[100:101]
	v_pk_mul_f32 v[90:91], v[90:91], v[136:137] op_sel_hi:[1,0]
	v_cvt_pk_bf16_f32 v99, v100, v101
	v_lshl_add_u64 v[100:101], v[132:133], 1, s[2:3]
	ds_write_b64 v165, v[98:99] offset:2048
	v_mul_f32_e32 v98, 0xbfb8aa3b, v90
	v_mul_f32_e32 v99, 0xbfb8aa3b, v91
	v_exp_f32_e32 v98, v98
	v_exp_f32_e32 v99, v99
	v_pk_mul_f32 v[92:93], v[92:93], v[136:137] op_sel_hi:[1,0]
	v_pk_mul_f32 v[94:95], v[94:95], v[136:137] op_sel_hi:[1,0]
	v_add_f32_e32 v98, 1.0, v98
	v_add_f32_e32 v99, 1.0, v99
	v_mul_f32_e32 v101, 0xbfb8aa3b, v92
	v_mul_f32_e32 v102, 0xbfb8aa3b, v93
	v_rcp_f32_e32 v98, v98
	v_rcp_f32_e32 v99, v99
	v_exp_f32_e32 v101, v101
	v_exp_f32_e32 v102, v102
	v_pk_mul_f32 v[82:83], v[82:83], v[122:123] op_sel_hi:[1,0]
	v_pk_mul_f32 v[90:91], v[90:91], v[98:99]
	v_add_f32_e32 v98, 1.0, v101
	v_add_f32_e32 v99, 1.0, v102
	v_rcp_f32_e32 v98, v98
	v_rcp_f32_e32 v99, v99
	v_pk_mul_f32 v[90:91], v[94:95], v[90:91]
	v_pk_mul_f32 v[94:95], v[96:97], v[136:137] op_sel_hi:[1,0]
	v_or_b32_e32 v100, 32, v146
	v_pk_mul_f32 v[92:93], v[92:93], v[98:99]
	v_add_u32_e32 v132, v100, v123
	v_pk_mul_f32 v[92:93], v[94:95], v[92:93]
	v_mul_f32_e32 v94, 0xbfb8aa3b, v82
	v_mul_f32_e32 v95, 0xbfb8aa3b, v83
	v_exp_f32_e32 v94, v94
	v_exp_f32_e32 v95, v95
	v_cvt_pk_bf16_f32 v90, v90, v91
	v_cvt_pk_bf16_f32 v91, v92, v93
	v_lshl_add_u64 v[92:93], v[132:133], 1, s[2:3]
	v_pk_mul_f32 v[84:85], v[84:85], v[122:123] op_sel_hi:[1,0]
	ds_write_b64 v166, v[90:91]
	v_add_f32_e32 v90, 1.0, v94
	v_add_f32_e32 v91, 1.0, v95
	v_mul_f32_e32 v92, 0xbfb8aa3b, v84
	v_mul_f32_e32 v93, 0xbfb8aa3b, v85
	v_rcp_f32_e32 v90, v90
	v_rcp_f32_e32 v91, v91
	v_exp_f32_e32 v92, v92
	v_exp_f32_e32 v93, v93
	v_pk_mul_f32 v[86:87], v[86:87], v[122:123] op_sel_hi:[1,0]
	v_pk_mul_f32 v[82:83], v[82:83], v[90:91]
	v_add_f32_e32 v90, 1.0, v92
	v_add_f32_e32 v91, 1.0, v93
	v_rcp_f32_e32 v90, v90
	v_rcp_f32_e32 v91, v91
	v_pk_mul_f32 v[82:83], v[86:87], v[82:83]
	v_pk_mul_f32 v[86:87], v[88:89], v[122:123] op_sel_hi:[1,0]
	v_add_u32_e32 v132, v100, v118
	v_pk_mul_f32 v[84:85], v[84:85], v[90:91]
	v_cvt_pk_bf16_f32 v82, v82, v83
	v_pk_mul_f32 v[84:85], v[86:87], v[84:85]
	v_pk_mul_f32 v[74:75], v[74:75], v[136:137] op_sel_hi:[1,0]
	v_cvt_pk_bf16_f32 v83, v84, v85
	v_lshl_add_u64 v[84:85], v[132:133], 1, s[2:3]
	ds_write_b64 v166, v[82:83] offset:2048
	v_mul_f32_e32 v82, 0xbfb8aa3b, v74
	v_mul_f32_e32 v83, 0xbfb8aa3b, v75
	v_exp_f32_e32 v82, v82
	v_exp_f32_e32 v83, v83
	v_pk_mul_f32 v[76:77], v[76:77], v[136:137] op_sel_hi:[1,0]
	v_pk_mul_f32 v[78:79], v[78:79], v[136:137] op_sel_hi:[1,0]
	v_add_f32_e32 v82, 1.0, v82
	v_add_f32_e32 v83, 1.0, v83
	v_mul_f32_e32 v85, 0xbfb8aa3b, v76
	v_mul_f32_e32 v86, 0xbfb8aa3b, v77
	v_rcp_f32_e32 v82, v82
	v_rcp_f32_e32 v83, v83
	v_exp_f32_e32 v85, v85
	v_exp_f32_e32 v86, v86
	v_pk_mul_f32 v[66:67], v[66:67], v[122:123] op_sel_hi:[1,0]
	v_pk_mul_f32 v[74:75], v[74:75], v[82:83]
	v_add_f32_e32 v82, 1.0, v85
	v_add_f32_e32 v83, 1.0, v86
	v_rcp_f32_e32 v82, v82
	v_rcp_f32_e32 v83, v83
	v_pk_mul_f32 v[74:75], v[78:79], v[74:75]
	v_pk_mul_f32 v[78:79], v[80:81], v[136:137] op_sel_hi:[1,0]
	v_or_b32_e32 v84, 48, v146
	v_pk_mul_f32 v[76:77], v[76:77], v[82:83]
	v_add_u32_e32 v132, v84, v123
	v_pk_mul_f32 v[76:77], v[78:79], v[76:77]
	v_mul_f32_e32 v78, 0xbfb8aa3b, v66
	v_mul_f32_e32 v79, 0xbfb8aa3b, v67
	v_exp_f32_e32 v78, v78
	v_exp_f32_e32 v79, v79
	v_cvt_pk_bf16_f32 v74, v74, v75
	v_cvt_pk_bf16_f32 v75, v76, v77
	v_lshl_add_u64 v[76:77], v[132:133], 1, s[2:3]
	v_pk_mul_f32 v[68:69], v[68:69], v[122:123] op_sel_hi:[1,0]
	ds_write_b64 v167, v[74:75]
	v_add_f32_e32 v74, 1.0, v78
	v_add_f32_e32 v75, 1.0, v79
	v_mul_f32_e32 v76, 0xbfb8aa3b, v68
	v_mul_f32_e32 v77, 0xbfb8aa3b, v69
	v_rcp_f32_e32 v74, v74
	v_rcp_f32_e32 v75, v75
	v_exp_f32_e32 v76, v76
	v_exp_f32_e32 v77, v77
	v_pk_mul_f32 v[70:71], v[70:71], v[122:123] op_sel_hi:[1,0]
	v_pk_mul_f32 v[66:67], v[66:67], v[74:75]
	v_add_f32_e32 v74, 1.0, v76
	v_add_f32_e32 v75, 1.0, v77
	v_rcp_f32_e32 v74, v74
	v_rcp_f32_e32 v75, v75
	v_pk_mul_f32 v[66:67], v[70:71], v[66:67]
	v_pk_mul_f32 v[70:71], v[72:73], v[122:123] op_sel_hi:[1,0]
	s_waitcnt lgkmcnt(0)
	v_pk_mul_f32 v[58:59], v[58:59], v[134:135] op_sel_hi:[1,0]
	v_pk_mul_f32 v[68:69], v[68:69], v[74:75]
	v_add_u32_e32 v132, v84, v118
	v_pk_mul_f32 v[68:69], v[70:71], v[68:69]
	v_mul_f32_e32 v70, 0xbfb8aa3b, v58
	v_mul_f32_e32 v71, 0xbfb8aa3b, v59
	v_exp_f32_e32 v70, v70
	v_exp_f32_e32 v71, v71
	v_cvt_pk_bf16_f32 v66, v66, v67
	v_cvt_pk_bf16_f32 v67, v68, v69
	v_lshl_add_u64 v[68:69], v[132:133], 1, s[2:3]
	v_pk_mul_f32 v[60:61], v[60:61], v[134:135] op_sel_hi:[1,0]
	ds_write_b64 v167, v[66:67] offset:2048
	s_waitcnt lgkmcnt(0)
	ds_read_b128 v[172:175], v168
	ds_read_b128 v[176:179], v168 offset:1024
	ds_read_b128 v[180:183], v168 offset:2048
	ds_read_b128 v[184:187], v168 offset:3072
	v_add_u32_e32 v204, 0x16000, v169
	v_add_u32_e32 v205, 0x2c000, v169
	v_add_u32_e32 v206, 0x42000, v169
	s_waitcnt lgkmcnt(3)
; DEVI float silu(float x) { return x * __builtin_amdgcn_rcpf(1.f + __expf(-x)); }
; template <int EPI, int NRM>
; DEVI void epilogue(acc_t& acc, int pn, int trow, const EpiArgs& e, const float* rl, bf16* shmx) {
;     ...
;           float r[4];
; #pragma unroll
;           for (int j = 0; j < 4; ++j) r[j] = silu(acc[0][bj][m][n][j] * rs[bj][n]) * (acc[1][bj][m][n][j] * rs[bj][n]);
;           uint2 o; o.x = pack2(r[0], r[1]); o.y = pack2(r[2], r[3]);
;           const unsigned off = (unsigned)((tk0 + bj * 128 + n * 16) * DFF + pn * 128 + m * 16 + fl0);
;           *reinterpret_cast<uint2*>(e.o0 + off) = o;
	global_store_dwordx4 v169, v[172:175], s[2:3] nt
	s_waitcnt lgkmcnt(2)
	global_store_dwordx4 v204, v[176:179], s[2:3] nt
	s_waitcnt lgkmcnt(1)
	global_store_dwordx4 v205, v[180:183], s[2:3] nt
	s_waitcnt lgkmcnt(0)
	global_store_dwordx4 v206, v[184:187], s[2:3] nt
	v_add_f32_e32 v66, 1.0, v70
	v_add_f32_e32 v67, 1.0, v71
	v_mul_f32_e32 v68, 0xbfb8aa3b, v60
	v_mul_f32_e32 v69, 0xbfb8aa3b, v61
	v_rcp_f32_e32 v66, v66
	v_rcp_f32_e32 v67, v67
	v_exp_f32_e32 v68, v68
	v_exp_f32_e32 v69, v69
	v_pk_mul_f32 v[62:63], v[62:63], v[134:135] op_sel_hi:[1,0]
	v_pk_mul_f32 v[58:59], v[58:59], v[66:67]
	v_add_f32_e32 v66, 1.0, v68
	v_add_f32_e32 v67, 1.0, v69
	v_rcp_f32_e32 v66, v66
	v_rcp_f32_e32 v67, v67
	v_pk_mul_f32 v[58:59], v[62:63], v[58:59]
	v_pk_mul_f32 v[42:43], v[42:43], v[134:135] op_sel_hi:[1,0]
	v_cvt_pk_bf16_f32 v62, v58, v59
	v_pk_mul_f32 v[58:59], v[60:61], v[66:67]
	v_pk_mul_f32 v[60:61], v[64:65], v[134:135] op_sel_hi:[1,0]
	v_pk_mul_f32 v[44:45], v[44:45], v[134:135] op_sel_hi:[1,0]
	v_pk_mul_f32 v[58:59], v[60:61], v[58:59]
	v_pk_mul_f32 v[46:47], v[46:47], v[134:135] op_sel_hi:[1,0]
	v_cvt_pk_bf16_f32 v63, v58, v59
	v_add_u32_e32 v59, 0xb0000, v123
	v_mov_b32_e32 v58, v135
	v_pk_mul_f32 v[50:51], v[50:51], v[58:59] op_sel_hi:[1,0]
	v_add_u32_e32 v132, v59, v146
	v_mul_f32_e32 v64, 0xbfb8aa3b, v50
	v_mul_f32_e32 v65, 0xbfb8aa3b, v51
	v_exp_f32_e32 v64, v64
	v_exp_f32_e32 v65, v65
	v_lshl_add_u64 v[60:61], v[132:133], 1, s[2:3]
	v_pk_mul_f32 v[52:53], v[52:53], v[58:59] op_sel_hi:[1,0]
	ds_write_b64 v164, v[62:63] offset:4096
	v_add_f32_e32 v60, 1.0, v64
	v_add_f32_e32 v61, 1.0, v65
	v_mul_f32_e32 v62, 0xbfb8aa3b, v52
	v_mul_f32_e32 v63, 0xbfb8aa3b, v53
	v_rcp_f32_e32 v60, v60
	v_rcp_f32_e32 v61, v61
	v_exp_f32_e32 v62, v62
	v_exp_f32_e32 v63, v63
	v_pk_mul_f32 v[54:55], v[54:55], v[58:59] op_sel_hi:[1,0]
	v_pk_mul_f32 v[50:51], v[50:51], v[60:61]
	v_add_f32_e32 v60, 1.0, v62
	v_add_f32_e32 v61, 1.0, v63
	v_rcp_f32_e32 v60, v60
	v_rcp_f32_e32 v61, v61
	v_pk_mul_f32 v[50:51], v[54:55], v[50:51]
	v_pk_mul_f32 v[54:55], v[56:57], v[58:59] op_sel_hi:[1,0]
	v_mul_f32_e32 v56, 0xbfb8aa3b, v43
	v_pk_mul_f32 v[52:53], v[52:53], v[60:61]
	v_exp_f32_e32 v56, v56
	v_pk_mul_f32 v[52:53], v[54:55], v[52:53]
	v_mul_f32_e32 v55, 0xbfb8aa3b, v42
	v_exp_f32_e32 v55, v55
	v_add_u32_e32 v54, 0xc6000, v123
	v_add_u32_e32 v132, v54, v146
	v_cvt_pk_bf16_f32 v50, v50, v51
	v_cvt_pk_bf16_f32 v51, v52, v53
	v_lshl_add_u64 v[52:53], v[132:133], 1, s[2:3]
	ds_write_b64 v164, v[50:51] offset:6144
	v_add_f32_e32 v50, 1.0, v55
	v_add_f32_e32 v51, 1.0, v56
	v_mul_f32_e32 v52, 0xbfb8aa3b, v44
	v_mul_f32_e32 v53, 0xbfb8aa3b, v45
	v_rcp_f32_e32 v50, v50
	v_rcp_f32_e32 v51, v51
	v_exp_f32_e32 v52, v52
	v_exp_f32_e32 v53, v53
	v_pk_mul_f32 v[34:35], v[34:35], v[58:59] op_sel_hi:[1,0]
	v_pk_mul_f32 v[42:43], v[42:43], v[50:51]
	v_add_f32_e32 v50, 1.0, v52
	v_add_f32_e32 v51, 1.0, v53
	v_rcp_f32_e32 v50, v50
	v_rcp_f32_e32 v51, v51
	v_pk_mul_f32 v[42:43], v[46:47], v[42:43]
	v_pk_mul_f32 v[46:47], v[48:49], v[134:135] op_sel_hi:[1,0]
	v_add_u32_e32 v132, v116, v59
	v_pk_mul_f32 v[44:45], v[44:45], v[50:51]
	v_cvt_pk_bf16_f32 v42, v42, v43
	v_pk_mul_f32 v[44:45], v[46:47], v[44:45]
	v_mul_f32_e32 v46, 0xbfb8aa3b, v34
	v_mul_f32_e32 v47, 0xbfb8aa3b, v35
	v_exp_f32_e32 v46, v46
	v_exp_f32_e32 v47, v47
	v_cvt_pk_bf16_f32 v43, v44, v45
	v_lshl_add_u64 v[44:45], v[132:133], 1, s[2:3]
	v_pk_mul_f32 v[36:37], v[36:37], v[58:59] op_sel_hi:[1,0]
	ds_write_b64 v165, v[42:43] offset:4096
	v_add_f32_e32 v42, 1.0, v46
	v_add_f32_e32 v43, 1.0, v47
	v_mul_f32_e32 v44, 0xbfb8aa3b, v36
	v_mul_f32_e32 v45, 0xbfb8aa3b, v37
	v_rcp_f32_e32 v42, v42
	v_rcp_f32_e32 v43, v43
	v_exp_f32_e32 v44, v44
	v_exp_f32_e32 v45, v45
	v_pk_mul_f32 v[38:39], v[38:39], v[58:59] op_sel_hi:[1,0]
	v_pk_mul_f32 v[34:35], v[34:35], v[42:43]
	v_add_f32_e32 v42, 1.0, v44
	v_add_f32_e32 v43, 1.0, v45
	v_rcp_f32_e32 v42, v42
	v_rcp_f32_e32 v43, v43
	v_pk_mul_f32 v[34:35], v[38:39], v[34:35]
	v_pk_mul_f32 v[38:39], v[40:41], v[58:59] op_sel_hi:[1,0]
	v_pk_mul_f32 v[26:27], v[26:27], v[134:135] op_sel_hi:[1,0]
	v_pk_mul_f32 v[36:37], v[36:37], v[42:43]
	v_add_u32_e32 v132, v116, v54
	v_pk_mul_f32 v[36:37], v[38:39], v[36:37]
	v_mul_f32_e32 v38, 0xbfb8aa3b, v26
	v_mul_f32_e32 v39, 0xbfb8aa3b, v27
	v_exp_f32_e32 v38, v38
	v_exp_f32_e32 v39, v39
	v_cvt_pk_bf16_f32 v34, v34, v35
	v_cvt_pk_bf16_f32 v35, v36, v37
	v_lshl_add_u64 v[36:37], v[132:133], 1, s[2:3]
	v_pk_mul_f32 v[28:29], v[28:29], v[134:135] op_sel_hi:[1,0]
	ds_write_b64 v165, v[34:35] offset:6144
	v_add_f32_e32 v34, 1.0, v38
	v_add_f32_e32 v35, 1.0, v39
; DEVI float silu(float x) { return x * __builtin_amdgcn_rcpf(1.f + __expf(-x)); }
; template <int EPI, int NRM>
; DEVI void epilogue(acc_t& acc, int pn, int trow, const EpiArgs& e, const float* rl, bf16* shmx) {
;     ...
;   } else if constexpr (EPI == EPI_SWIGLU) {
; #pragma unroll
;     for (int bj = 0; bj < 2; ++bj)
; #pragma unroll
;       for (int m = 0; m < 4; ++m)
; #pragma unroll
;         for (int n = 0; n < 2; ++n) {
;           float r[4];
; #pragma unroll
;           for (int j = 0; j < 4; ++j) r[j] = silu(acc[0][bj][m][n][j] * rs[bj][n]) * (acc[1][bj][m][n][j] * rs[bj][n]);
;           uint2 o; o.x = pack2(r[0], r[1]); o.y = pack2(r[2], r[3]);
;           const unsigned off = (unsigned)((tk0 + bj * 128 + n * 16) * DFF + pn * 128 + m * 16 + fl0);
;           *reinterpret_cast<uint2*>(e.o0 + off) = o;
;         }
	v_mul_f32_e32 v36, 0xbfb8aa3b, v28
	v_mul_f32_e32 v37, 0xbfb8aa3b, v29
	v_rcp_f32_e32 v34, v34
	v_rcp_f32_e32 v35, v35
	v_exp_f32_e32 v36, v36
	v_exp_f32_e32 v37, v37
	v_pk_mul_f32 v[30:31], v[30:31], v[134:135] op_sel_hi:[1,0]
	v_pk_mul_f32 v[26:27], v[26:27], v[34:35]
	v_add_f32_e32 v34, 1.0, v36
	v_add_f32_e32 v35, 1.0, v37
	v_rcp_f32_e32 v34, v34
	v_rcp_f32_e32 v35, v35
	v_pk_mul_f32 v[26:27], v[30:31], v[26:27]
	v_pk_mul_f32 v[30:31], v[32:33], v[134:135] op_sel_hi:[1,0]
	v_pk_mul_f32 v[18:19], v[18:19], v[58:59] op_sel_hi:[1,0]
	v_pk_mul_f32 v[28:29], v[28:29], v[34:35]
	v_add_u32_e32 v132, v100, v59
	v_pk_mul_f32 v[28:29], v[30:31], v[28:29]
	v_mul_f32_e32 v30, 0xbfb8aa3b, v18
	v_mul_f32_e32 v31, 0xbfb8aa3b, v19
	v_exp_f32_e32 v30, v30
	v_exp_f32_e32 v31, v31
	v_cvt_pk_bf16_f32 v26, v26, v27
	v_cvt_pk_bf16_f32 v27, v28, v29
	v_lshl_add_u64 v[28:29], v[132:133], 1, s[2:3]
	v_pk_mul_f32 v[20:21], v[20:21], v[58:59] op_sel_hi:[1,0]
	ds_write_b64 v166, v[26:27] offset:4096
	v_add_f32_e32 v26, 1.0, v30
	v_add_f32_e32 v27, 1.0, v31
	v_mul_f32_e32 v28, 0xbfb8aa3b, v20
	v_mul_f32_e32 v29, 0xbfb8aa3b, v21
	v_rcp_f32_e32 v26, v26
	v_rcp_f32_e32 v27, v27
	v_exp_f32_e32 v28, v28
	v_exp_f32_e32 v29, v29
	v_pk_mul_f32 v[22:23], v[22:23], v[58:59] op_sel_hi:[1,0]
	v_pk_mul_f32 v[18:19], v[18:19], v[26:27]
	v_add_f32_e32 v26, 1.0, v28
	v_add_f32_e32 v27, 1.0, v29
	v_rcp_f32_e32 v26, v26
	v_rcp_f32_e32 v27, v27
	v_pk_mul_f32 v[18:19], v[22:23], v[18:19]
	v_pk_mul_f32 v[22:23], v[24:25], v[58:59] op_sel_hi:[1,0]
	v_pk_mul_f32 v[10:11], v[10:11], v[134:135] op_sel_hi:[1,0]
	v_pk_mul_f32 v[20:21], v[20:21], v[26:27]
	v_add_u32_e32 v132, v100, v54
	v_pk_mul_f32 v[20:21], v[22:23], v[20:21]
	v_mul_f32_e32 v22, 0xbfb8aa3b, v10
	v_mul_f32_e32 v23, 0xbfb8aa3b, v11
	v_exp_f32_e32 v22, v22
	v_exp_f32_e32 v23, v23
	v_cvt_pk_bf16_f32 v18, v18, v19
	v_cvt_pk_bf16_f32 v19, v20, v21
	v_lshl_add_u64 v[20:21], v[132:133], 1, s[2:3]
	v_pk_mul_f32 v[12:13], v[12:13], v[134:135] op_sel_hi:[1,0]
	ds_write_b64 v166, v[18:19] offset:6144
	v_add_f32_e32 v18, 1.0, v22
	v_add_f32_e32 v19, 1.0, v23
	v_mul_f32_e32 v20, 0xbfb8aa3b, v12
	v_mul_f32_e32 v21, 0xbfb8aa3b, v13
	v_rcp_f32_e32 v18, v18
	v_rcp_f32_e32 v19, v19
	v_exp_f32_e32 v20, v20
	v_exp_f32_e32 v21, v21
	v_pk_mul_f32 v[14:15], v[14:15], v[134:135] op_sel_hi:[1,0]
	v_pk_mul_f32 v[10:11], v[10:11], v[18:19]
	v_add_f32_e32 v18, 1.0, v20
	v_add_f32_e32 v19, 1.0, v21
	v_rcp_f32_e32 v18, v18
	v_rcp_f32_e32 v19, v19
	v_pk_mul_f32 v[10:11], v[14:15], v[10:11]
	v_pk_mul_f32 v[14:15], v[16:17], v[134:135] op_sel_hi:[1,0]
	v_pk_mul_f32 v[2:3], v[2:3], v[58:59] op_sel_hi:[1,0]
	v_pk_mul_f32 v[12:13], v[12:13], v[18:19]
	v_add_u32_e32 v132, v84, v59
	v_pk_mul_f32 v[12:13], v[14:15], v[12:13]
	v_mul_f32_e32 v14, 0xbfb8aa3b, v2
	v_mul_f32_e32 v15, 0xbfb8aa3b, v3
	v_exp_f32_e32 v14, v14
	v_exp_f32_e32 v15, v15
	v_cvt_pk_bf16_f32 v10, v10, v11
	v_cvt_pk_bf16_f32 v11, v12, v13
	v_lshl_add_u64 v[12:13], v[132:133], 1, s[2:3]
	v_pk_mul_f32 v[4:5], v[4:5], v[58:59] op_sel_hi:[1,0]
	ds_write_b64 v167, v[10:11] offset:4096
	v_add_f32_e32 v10, 1.0, v14
	v_add_f32_e32 v11, 1.0, v15
	v_mul_f32_e32 v12, 0xbfb8aa3b, v4
	v_mul_f32_e32 v13, 0xbfb8aa3b, v5
	v_rcp_f32_e32 v10, v10
	v_rcp_f32_e32 v11, v11
	v_exp_f32_e32 v12, v12
	v_exp_f32_e32 v13, v13
	v_pk_mul_f32 v[6:7], v[6:7], v[58:59] op_sel_hi:[1,0]
	v_pk_mul_f32 v[2:3], v[2:3], v[10:11]
	v_add_f32_e32 v10, 1.0, v12
	v_add_f32_e32 v11, 1.0, v13
	v_rcp_f32_e32 v10, v10
	v_rcp_f32_e32 v11, v11
	v_pk_mul_f32 v[2:3], v[6:7], v[2:3]
	v_pk_mul_f32 v[6:7], v[8:9], v[58:59] op_sel_hi:[1,0]
	v_add_u32_e32 v132, v84, v54
	v_pk_mul_f32 v[4:5], v[4:5], v[10:11]
	v_cvt_pk_bf16_f32 v2, v2, v3
	v_pk_mul_f32 v[4:5], v[6:7], v[4:5]
	s_add_i32 s16, s16, 1
	v_cvt_pk_bf16_f32 v3, v4, v5
	v_lshl_add_u64 v[4:5], v[132:133], 1, s[2:3]
	s_andn2_b64 vcc, exec, s[4:5]
	s_mov_b32 s14, s8
	s_mov_b32 s12, s10
	ds_write_b64 v167, v[2:3] offset:6144
	s_waitcnt lgkmcnt(0)
	ds_read_b128 v[188:191], v168 offset:4096
	ds_read_b128 v[192:195], v168 offset:5120
	ds_read_b128 v[196:199], v168 offset:6144
	ds_read_b128 v[200:203], v168 offset:7168
	v_add_u32_e32 v207, 0x160000, v169
	v_add_u32_e32 v208, 0x176000, v169
	v_add_u32_e32 v209, 0x18c000, v169
	v_add_u32_e32 v210, 0x1a2000, v169
	s_waitcnt lgkmcnt(3)
	global_store_dwordx4 v207, v[188:191], s[2:3] nt
	s_waitcnt lgkmcnt(2)
	global_store_dwordx4 v208, v[192:195], s[2:3] nt
	s_waitcnt lgkmcnt(1)
	global_store_dwordx4 v209, v[196:199], s[2:3] nt
	s_waitcnt lgkmcnt(0)
	global_store_dwordx4 v210, v[200:203], s[2:3] nt
	s_cbranch_vccz .LBB0_1668

; DEVI float silu(float x) { return x * __builtin_amdgcn_rcpf(1.f + __expf(-x)); }
; template <int EPI, int NRM>
; DEVI void epilogue(acc_t& acc, int pn, int trow, const EpiArgs& e, const float* rl, bf16* shmx) {
;     ...
;   const int fl0 = wr * 64 + fq * 4;
;   const int tk0 = trow + wc * 32 + fr;
;   float rs[2][2];
;   if constexpr (NRM) {
; #pragma unroll
;     for (int bj = 0; bj < 2; ++bj)
; #pragma unroll
;       for (int n = 0; n < 2; ++n) rs[bj][n] = rl[wc * 32 + fr + bj * 128 + n * 16];
;     ...
;   } else if constexpr (EPI == EPI_SWIGLU) {
; #pragma unroll
;     for (int bj = 0; bj < 2; ++bj)
; #pragma unroll
;       for (int m = 0; m < 4; ++m)
; #pragma unroll
;         for (int n = 0; n < 2; ++n) {
;           float r[4];
; #pragma unroll
;           for (int j = 0; j < 4; ++j) r[j] = silu(acc[0][bj][m][n][j] * rs[bj][n]) * (acc[1][bj][m][n][j] * rs[bj][n]);
;           uint2 o; o.x = pack2(r[0], r[1]); o.y = pack2(r[2], r[3]);
;           const unsigned off = (unsigned)((tk0 + bj * 128 + n * 16) * DFF + pn * 128 + m * 16 + fl0);
;           *reinterpret_cast<uint2*>(e.o0 + off) = o;
;         }
.LBB0_2055:
	v_and_b32_e32 v170, 15, v1
	v_bfe_u32 v171, v1, 4, 2
	v_lshrrev_b32_e32 v172, 6, v1
	v_and_b32_e32 v173, 3, v172
	v_lshrrev_b32_e32 v174, 2, v172
	v_lshlrev_b32_e32 v175, 13, v173
	v_lshl_add_u32 v175, v174, 16, v175
	v_add_u32_e32 v175, 0x8000, v175
	v_lshl_add_u32 v176, v170, 7, v175
	v_and_b32_e32 v177, 1, v171
	v_lshl_add_u32 v176, v177, 3, v176
	v_lshrrev_b32_e32 v177, 1, v171
	v_and_b32_e32 v178, 7, v170
	v_add_u32_e32 v179, 0, v177
	v_xor_b32_e32 v179, v179, v178
	v_lshl_add_u32 v164, v179, 4, v176
	v_add_u32_e32 v179, 2, v177
	v_xor_b32_e32 v179, v179, v178
	v_lshl_add_u32 v165, v179, 4, v176
	v_add_u32_e32 v179, 4, v177
	v_xor_b32_e32 v179, v179, v178
	v_lshl_add_u32 v166, v179, 4, v176
	v_add_u32_e32 v179, 6, v177
	v_xor_b32_e32 v179, v179, v178
	v_lshl_add_u32 v167, v179, 4, v176
	v_and_b32_e32 v180, 63, v1
	v_lshl_add_u32 v168, v180, 4, v175
	v_lshrrev_b32_e32 v181, 3, v180
	v_and_b32_e32 v182, 7, v180
	v_xor_b32_e32 v182, v182, v181
	s_lshl_b32 s9, s12, 8
	v_lshl_add_u32 v183, v173, 5, v181
	v_add_u32_e32 v183, s9, v183
	v_mul_u32_u24_e32 v183, 0x1600, v183
	s_lshl_b32 s9, s14, 7
	v_lshl_add_u32 v179, v174, 6, s9
	v_lshl_add_u32 v179, v182, 3, v179
	v_add_lshl_u32 v169, v183, v179, 1
	v_mov_b32_e32 v132, v1
	s_lshl_b32 s11, s16, 10
	s_and_b32 s11, s11, 0x400
	v_and_b32_e32 v141, 15, v132
	v_ashrrev_i32_e32 v142, 2, v132
	v_lshrrev_b32_e32 v143, 2, v132
	v_lshrrev_b32_e32 v132, 1, v132
	s_add_i32 s11, s11, 0
	v_and_b32_e32 v132, 0x60, v132
	s_add_i32 s11, s11, 0x20000
	v_lshlrev_b32_e32 v134, 2, v132
	v_lshlrev_b32_e32 v135, 2, v141
	v_add3_u32 v134, s11, v134, v135
	ds_read2_b32 v[136:137], v134 offset1:16
	ds_read2_b32 v[134:135], v134 offset0:128 offset1:144
	s_lshl_b32 s9, s12, 8
	v_or3_b32 v132, v141, s9, v132
	s_lshl_b32 s9, s14, 7
	s_waitcnt lgkmcnt(1)
	v_pk_mul_f32 v[122:123], v[122:123], v[136:137] op_sel_hi:[1,0]
	v_and_or_b32 v141, v143, 12, s9
	v_mul_f32_e32 v143, 0xbfb8aa3b, v122
	v_mul_f32_e32 v144, 0xbfb8aa3b, v123
	v_exp_f32_e32 v143, v143
	v_exp_f32_e32 v144, v144
	v_and_b32_e32 v142, 0xffffffc0, v142
	v_pk_mul_f32 v[124:125], v[124:125], v[136:137] op_sel_hi:[1,0]
	v_add_u32_e32 v141, v141, v142
	v_add_f32_e32 v142, 1.0, v143
	v_add_f32_e32 v143, 1.0, v144
	v_mul_f32_e32 v144, 0xbfb8aa3b, v124
	v_mul_f32_e32 v145, 0xbfb8aa3b, v125
	v_rcp_f32_e32 v142, v142
	v_rcp_f32_e32 v143, v143
	v_exp_f32_e32 v144, v144
	v_exp_f32_e32 v145, v145
	v_pk_mul_f32 v[126:127], v[126:127], v[136:137] op_sel_hi:[1,0]
	v_pk_mul_f32 v[122:123], v[122:123], v[142:143]
	v_add_f32_e32 v142, 1.0, v144
	v_add_f32_e32 v143, 1.0, v145
	v_rcp_f32_e32 v142, v142
	v_rcp_f32_e32 v143, v143
	v_pk_mul_f32 v[122:123], v[126:127], v[122:123]
	v_pk_mul_f32 v[106:107], v[106:107], v[136:137] op_sel_hi:[1,0]
	v_cvt_pk_bf16_f32 v126, v122, v123
	v_pk_mul_f32 v[122:123], v[124:125], v[142:143]
	v_pk_mul_f32 v[124:125], v[128:129], v[136:137] op_sel_hi:[1,0]
	v_pk_mul_f32 v[108:109], v[108:109], v[136:137] op_sel_hi:[1,0]
	v_pk_mul_f32 v[122:123], v[124:125], v[122:123]
	v_pk_mul_f32 v[110:111], v[110:111], v[136:137] op_sel_hi:[1,0]
	v_cvt_pk_bf16_f32 v127, v122, v123
	v_mul_lo_u32 v123, v132, s41
	v_mov_b32_e32 v122, v137
	v_pk_mul_f32 v[114:115], v[114:115], v[122:123] op_sel_hi:[1,0]
	v_add_u32_e32 v132, v141, v123
	v_mul_f32_e32 v128, 0xbfb8aa3b, v114
	v_mul_f32_e32 v129, 0xbfb8aa3b, v115
	v_exp_f32_e32 v128, v128
	v_exp_f32_e32 v129, v129
	v_lshl_add_u64 v[124:125], v[132:133], 1, s[2:3]
	v_pk_mul_f32 v[116:117], v[116:117], v[122:123] op_sel_hi:[1,0]
	ds_write_b64 v164, v[126:127]
	v_add_f32_e32 v124, 1.0, v128
	v_add_f32_e32 v125, 1.0, v129
	v_mul_f32_e32 v126, 0xbfb8aa3b, v116
	v_mul_f32_e32 v127, 0xbfb8aa3b, v117
	v_rcp_f32_e32 v124, v124
	v_rcp_f32_e32 v125, v125
	v_exp_f32_e32 v126, v126
	v_exp_f32_e32 v127, v127
	v_pk_mul_f32 v[118:119], v[118:119], v[122:123] op_sel_hi:[1,0]
	v_pk_mul_f32 v[114:115], v[114:115], v[124:125]
	v_add_f32_e32 v124, 1.0, v126
	v_add_f32_e32 v125, 1.0, v127
	v_rcp_f32_e32 v124, v124
	v_rcp_f32_e32 v125, v125
	v_pk_mul_f32 v[114:115], v[118:119], v[114:115]
	v_pk_mul_f32 v[118:119], v[120:121], v[122:123] op_sel_hi:[1,0]
	v_cvt_pk_bf16_f32 v114, v114, v115
	v_pk_mul_f32 v[116:117], v[116:117], v[124:125]
	v_pk_mul_f32 v[98:99], v[98:99], v[122:123] op_sel_hi:[1,0]
	v_pk_mul_f32 v[116:117], v[118:119], v[116:117]
	v_add_u32_e32 v118, 0x16000, v123
	v_add_u32_e32 v132, v118, v141
	v_cvt_pk_bf16_f32 v115, v116, v117
	v_lshl_add_u64 v[116:117], v[132:133], 1, s[2:3]
	ds_write_b64 v164, v[114:115] offset:2048
	v_mul_f32_e32 v114, 0xbfb8aa3b, v106
	v_mul_f32_e32 v115, 0xbfb8aa3b, v107
	v_exp_f32_e32 v114, v114
	v_exp_f32_e32 v115, v115
	v_mul_f32_e32 v117, 0xbfb8aa3b, v108
	v_mul_f32_e32 v119, 0xbfb8aa3b, v109
	v_add_f32_e32 v114, 1.0, v114
	v_add_f32_e32 v115, 1.0, v115
	v_rcp_f32_e32 v114, v114
	v_rcp_f32_e32 v115, v115
	v_exp_f32_e32 v117, v117
	v_exp_f32_e32 v119, v119
	v_or_b32_e32 v116, 16, v141
	v_pk_mul_f32 v[106:107], v[106:107], v[114:115]
	v_add_f32_e32 v114, 1.0, v117
	v_add_f32_e32 v115, 1.0, v119
	v_rcp_f32_e32 v114, v114
	v_rcp_f32_e32 v115, v115
	v_pk_mul_f32 v[106:107], v[110:111], v[106:107]
	v_pk_mul_f32 v[110:111], v[112:113], v[136:137] op_sel_hi:[1,0]
	v_add_u32_e32 v132, v116, v123
	v_pk_mul_f32 v[108:109], v[108:109], v[114:115]
	v_cvt_pk_bf16_f32 v106, v106, v107
	v_pk_mul_f32 v[108:109], v[110:111], v[108:109]
	v_mul_f32_e32 v110, 0xbfb8aa3b, v98
	v_mul_f32_e32 v111, 0xbfb8aa3b, v99
	v_exp_f32_e32 v110, v110
	v_exp_f32_e32 v111, v111
	v_cvt_pk_bf16_f32 v107, v108, v109
	v_lshl_add_u64 v[108:109], v[132:133], 1, s[2:3]
	v_pk_mul_f32 v[100:101], v[100:101], v[122:123] op_sel_hi:[1,0]
; DEVI float silu(float x) { return x * __builtin_amdgcn_rcpf(1.f + __expf(-x)); }
; template <int EPI, int NRM>
; DEVI void epilogue(acc_t& acc, int pn, int trow, const EpiArgs& e, const float* rl, bf16* shmx) {
;     ...
;   } else if constexpr (EPI == EPI_SWIGLU) {
; #pragma unroll
;     for (int bj = 0; bj < 2; ++bj)
; #pragma unroll
;       for (int m = 0; m < 4; ++m)
; #pragma unroll
;         for (int n = 0; n < 2; ++n) {
;           float r[4];
; #pragma unroll
;           for (int j = 0; j < 4; ++j) r[j] = silu(acc[0][bj][m][n][j] * rs[bj][n]) * (acc[1][bj][m][n][j] * rs[bj][n]);
;           uint2 o; o.x = pack2(r[0], r[1]); o.y = pack2(r[2], r[3]);
;           const unsigned off = (unsigned)((tk0 + bj * 128 + n * 16) * DFF + pn * 128 + m * 16 + fl0);
;           *reinterpret_cast<uint2*>(e.o0 + off) = o;
;         }
	ds_write_b64 v165, v[106:107]
	v_add_f32_e32 v106, 1.0, v110
	v_add_f32_e32 v107, 1.0, v111
	v_mul_f32_e32 v108, 0xbfb8aa3b, v100
	v_mul_f32_e32 v109, 0xbfb8aa3b, v101
	v_rcp_f32_e32 v106, v106
	v_rcp_f32_e32 v107, v107
	v_exp_f32_e32 v108, v108
	v_exp_f32_e32 v109, v109
	v_pk_mul_f32 v[102:103], v[102:103], v[122:123] op_sel_hi:[1,0]
	v_pk_mul_f32 v[98:99], v[98:99], v[106:107]
	v_add_f32_e32 v106, 1.0, v108
	v_add_f32_e32 v107, 1.0, v109
	v_rcp_f32_e32 v106, v106
	v_rcp_f32_e32 v107, v107
	v_pk_mul_f32 v[98:99], v[102:103], v[98:99]
	v_pk_mul_f32 v[102:103], v[104:105], v[122:123] op_sel_hi:[1,0]
	v_add_u32_e32 v132, v116, v118
	v_pk_mul_f32 v[100:101], v[100:101], v[106:107]
	v_cvt_pk_bf16_f32 v98, v98, v99
	v_pk_mul_f32 v[100:101], v[102:103], v[100:101]
	v_pk_mul_f32 v[90:91], v[90:91], v[136:137] op_sel_hi:[1,0]
	v_cvt_pk_bf16_f32 v99, v100, v101
	v_lshl_add_u64 v[100:101], v[132:133], 1, s[2:3]
	ds_write_b64 v165, v[98:99] offset:2048
	v_mul_f32_e32 v98, 0xbfb8aa3b, v90
	v_mul_f32_e32 v99, 0xbfb8aa3b, v91
	v_exp_f32_e32 v98, v98
	v_exp_f32_e32 v99, v99
	v_pk_mul_f32 v[92:93], v[92:93], v[136:137] op_sel_hi:[1,0]
	v_pk_mul_f32 v[94:95], v[94:95], v[136:137] op_sel_hi:[1,0]
	v_add_f32_e32 v98, 1.0, v98
	v_add_f32_e32 v99, 1.0, v99
	v_mul_f32_e32 v101, 0xbfb8aa3b, v92
	v_mul_f32_e32 v102, 0xbfb8aa3b, v93
	v_rcp_f32_e32 v98, v98
	v_rcp_f32_e32 v99, v99
	v_exp_f32_e32 v101, v101
	v_exp_f32_e32 v102, v102
	v_pk_mul_f32 v[82:83], v[82:83], v[122:123] op_sel_hi:[1,0]
	v_pk_mul_f32 v[90:91], v[90:91], v[98:99]
	v_add_f32_e32 v98, 1.0, v101
	v_add_f32_e32 v99, 1.0, v102
	v_rcp_f32_e32 v98, v98
	v_rcp_f32_e32 v99, v99
	v_pk_mul_f32 v[90:91], v[94:95], v[90:91]
	v_pk_mul_f32 v[94:95], v[96:97], v[136:137] op_sel_hi:[1,0]
	v_or_b32_e32 v100, 32, v141
	v_pk_mul_f32 v[92:93], v[92:93], v[98:99]
	v_add_u32_e32 v132, v100, v123
	v_pk_mul_f32 v[92:93], v[94:95], v[92:93]
	v_mul_f32_e32 v94, 0xbfb8aa3b, v82
	v_mul_f32_e32 v95, 0xbfb8aa3b, v83
	v_exp_f32_e32 v94, v94
	v_exp_f32_e32 v95, v95
	v_cvt_pk_bf16_f32 v90, v90, v91
	v_cvt_pk_bf16_f32 v91, v92, v93
	v_lshl_add_u64 v[92:93], v[132:133], 1, s[2:3]
	v_pk_mul_f32 v[84:85], v[84:85], v[122:123] op_sel_hi:[1,0]
	ds_write_b64 v166, v[90:91]
	v_add_f32_e32 v90, 1.0, v94
	v_add_f32_e32 v91, 1.0, v95
	v_mul_f32_e32 v92, 0xbfb8aa3b, v84
	v_mul_f32_e32 v93, 0xbfb8aa3b, v85
	v_rcp_f32_e32 v90, v90
	v_rcp_f32_e32 v91, v91
	v_exp_f32_e32 v92, v92
	v_exp_f32_e32 v93, v93
	v_pk_mul_f32 v[86:87], v[86:87], v[122:123] op_sel_hi:[1,0]
	v_pk_mul_f32 v[82:83], v[82:83], v[90:91]
	v_add_f32_e32 v90, 1.0, v92
	v_add_f32_e32 v91, 1.0, v93
	v_rcp_f32_e32 v90, v90
	v_rcp_f32_e32 v91, v91
	v_pk_mul_f32 v[82:83], v[86:87], v[82:83]
	v_pk_mul_f32 v[86:87], v[88:89], v[122:123] op_sel_hi:[1,0]
	v_add_u32_e32 v132, v100, v118
	v_pk_mul_f32 v[84:85], v[84:85], v[90:91]
	v_cvt_pk_bf16_f32 v82, v82, v83
	v_pk_mul_f32 v[84:85], v[86:87], v[84:85]
	v_pk_mul_f32 v[74:75], v[74:75], v[136:137] op_sel_hi:[1,0]
	v_cvt_pk_bf16_f32 v83, v84, v85
	v_lshl_add_u64 v[84:85], v[132:133], 1, s[2:3]
	ds_write_b64 v166, v[82:83] offset:2048
	v_mul_f32_e32 v82, 0xbfb8aa3b, v74
	v_mul_f32_e32 v83, 0xbfb8aa3b, v75
	v_exp_f32_e32 v82, v82
	v_exp_f32_e32 v83, v83
	v_pk_mul_f32 v[76:77], v[76:77], v[136:137] op_sel_hi:[1,0]
	v_pk_mul_f32 v[78:79], v[78:79], v[136:137] op_sel_hi:[1,0]
	v_add_f32_e32 v82, 1.0, v82
	v_add_f32_e32 v83, 1.0, v83
	v_mul_f32_e32 v85, 0xbfb8aa3b, v76
	v_mul_f32_e32 v86, 0xbfb8aa3b, v77
	v_rcp_f32_e32 v82, v82
	v_rcp_f32_e32 v83, v83
	v_exp_f32_e32 v85, v85
	v_exp_f32_e32 v86, v86
	v_pk_mul_f32 v[66:67], v[66:67], v[122:123] op_sel_hi:[1,0]
	v_pk_mul_f32 v[74:75], v[74:75], v[82:83]
	v_add_f32_e32 v82, 1.0, v85
	v_add_f32_e32 v83, 1.0, v86
	v_rcp_f32_e32 v82, v82
	v_rcp_f32_e32 v83, v83
	v_pk_mul_f32 v[74:75], v[78:79], v[74:75]
	v_pk_mul_f32 v[78:79], v[80:81], v[136:137] op_sel_hi:[1,0]
	v_or_b32_e32 v84, 48, v141
	v_pk_mul_f32 v[76:77], v[76:77], v[82:83]
	v_add_u32_e32 v132, v84, v123
	v_pk_mul_f32 v[76:77], v[78:79], v[76:77]
	v_mul_f32_e32 v78, 0xbfb8aa3b, v66
	v_mul_f32_e32 v79, 0xbfb8aa3b, v67
	v_exp_f32_e32 v78, v78
	v_exp_f32_e32 v79, v79
	v_cvt_pk_bf16_f32 v74, v74, v75
	v_cvt_pk_bf16_f32 v75, v76, v77
	v_lshl_add_u64 v[76:77], v[132:133], 1, s[2:3]
	v_pk_mul_f32 v[68:69], v[68:69], v[122:123] op_sel_hi:[1,0]
	ds_write_b64 v167, v[74:75]
	v_add_f32_e32 v74, 1.0, v78
	v_add_f32_e32 v75, 1.0, v79
	v_mul_f32_e32 v76, 0xbfb8aa3b, v68
	v_mul_f32_e32 v77, 0xbfb8aa3b, v69
	v_rcp_f32_e32 v74, v74
	v_rcp_f32_e32 v75, v75
	v_exp_f32_e32 v76, v76
	v_exp_f32_e32 v77, v77
	v_pk_mul_f32 v[70:71], v[70:71], v[122:123] op_sel_hi:[1,0]
	v_pk_mul_f32 v[66:67], v[66:67], v[74:75]
	v_add_f32_e32 v74, 1.0, v76
	v_add_f32_e32 v75, 1.0, v77
	v_rcp_f32_e32 v74, v74
	v_rcp_f32_e32 v75, v75
	v_pk_mul_f32 v[66:67], v[70:71], v[66:67]
	v_pk_mul_f32 v[70:71], v[72:73], v[122:123] op_sel_hi:[1,0]
	s_waitcnt lgkmcnt(0)
	v_pk_mul_f32 v[58:59], v[58:59], v[134:135] op_sel_hi:[1,0]
	v_pk_mul_f32 v[68:69], v[68:69], v[74:75]
	v_add_u32_e32 v132, v84, v118
	v_pk_mul_f32 v[68:69], v[70:71], v[68:69]
	v_mul_f32_e32 v70, 0xbfb8aa3b, v58
	v_mul_f32_e32 v71, 0xbfb8aa3b, v59
	v_exp_f32_e32 v70, v70
	v_exp_f32_e32 v71, v71
	v_cvt_pk_bf16_f32 v66, v66, v67
	v_cvt_pk_bf16_f32 v67, v68, v69
	v_lshl_add_u64 v[68:69], v[132:133], 1, s[2:3]
	v_pk_mul_f32 v[60:61], v[60:61], v[134:135] op_sel_hi:[1,0]
	ds_write_b64 v167, v[66:67] offset:2048
	s_waitcnt lgkmcnt(0)
	ds_read_b128 v[172:175], v168
	ds_read_b128 v[176:179], v168 offset:1024
	ds_read_b128 v[180:183], v168 offset:2048
	ds_read_b128 v[184:187], v168 offset:3072
	v_add_u32_e32 v204, 0x16000, v169
	v_add_u32_e32 v205, 0x2c000, v169
	v_add_u32_e32 v206, 0x42000, v169
	s_waitcnt lgkmcnt(3)
; DEVI float silu(float x) { return x * __builtin_amdgcn_rcpf(1.f + __expf(-x)); }
; template <int EPI, int NRM>
; DEVI void epilogue(acc_t& acc, int pn, int trow, const EpiArgs& e, const float* rl, bf16* shmx) {
;     ...
;           float r[4];
; #pragma unroll
;           for (int j = 0; j < 4; ++j) r[j] = silu(acc[0][bj][m][n][j] * rs[bj][n]) * (acc[1][bj][m][n][j] * rs[bj][n]);
;           uint2 o; o.x = pack2(r[0], r[1]); o.y = pack2(r[2], r[3]);
;           const unsigned off = (unsigned)((tk0 + bj * 128 + n * 16) * DFF + pn * 128 + m * 16 + fl0);
;           *reinterpret_cast<uint2*>(e.o0 + off) = o;
	global_store_dwordx4 v169, v[172:175], s[2:3] nt
	s_waitcnt lgkmcnt(2)
	global_store_dwordx4 v204, v[176:179], s[2:3] nt
	s_waitcnt lgkmcnt(1)
	global_store_dwordx4 v205, v[180:183], s[2:3] nt
	s_waitcnt lgkmcnt(0)
	global_store_dwordx4 v206, v[184:187], s[2:3] nt
	v_add_f32_e32 v66, 1.0, v70
	v_add_f32_e32 v67, 1.0, v71
	v_mul_f32_e32 v68, 0xbfb8aa3b, v60
	v_mul_f32_e32 v69, 0xbfb8aa3b, v61
	v_rcp_f32_e32 v66, v66
	v_rcp_f32_e32 v67, v67
	v_exp_f32_e32 v68, v68
	v_exp_f32_e32 v69, v69
	v_pk_mul_f32 v[62:63], v[62:63], v[134:135] op_sel_hi:[1,0]
	v_pk_mul_f32 v[58:59], v[58:59], v[66:67]
	v_add_f32_e32 v66, 1.0, v68
	v_add_f32_e32 v67, 1.0, v69
	v_rcp_f32_e32 v66, v66
	v_rcp_f32_e32 v67, v67
	v_pk_mul_f32 v[58:59], v[62:63], v[58:59]
	v_pk_mul_f32 v[42:43], v[42:43], v[134:135] op_sel_hi:[1,0]
	v_cvt_pk_bf16_f32 v62, v58, v59
	v_pk_mul_f32 v[58:59], v[60:61], v[66:67]
	v_pk_mul_f32 v[60:61], v[64:65], v[134:135] op_sel_hi:[1,0]
	v_pk_mul_f32 v[44:45], v[44:45], v[134:135] op_sel_hi:[1,0]
	v_pk_mul_f32 v[58:59], v[60:61], v[58:59]
	v_pk_mul_f32 v[46:47], v[46:47], v[134:135] op_sel_hi:[1,0]
	v_cvt_pk_bf16_f32 v63, v58, v59
	v_add_u32_e32 v59, 0xb0000, v123
	v_mov_b32_e32 v58, v135
	v_pk_mul_f32 v[50:51], v[50:51], v[58:59] op_sel_hi:[1,0]
	v_add_u32_e32 v132, v59, v141
	v_mul_f32_e32 v64, 0xbfb8aa3b, v50
	v_mul_f32_e32 v65, 0xbfb8aa3b, v51
	v_exp_f32_e32 v64, v64
	v_exp_f32_e32 v65, v65
	v_lshl_add_u64 v[60:61], v[132:133], 1, s[2:3]
	v_pk_mul_f32 v[52:53], v[52:53], v[58:59] op_sel_hi:[1,0]
	ds_write_b64 v164, v[62:63] offset:4096
	v_add_f32_e32 v60, 1.0, v64
	v_add_f32_e32 v61, 1.0, v65
	v_mul_f32_e32 v62, 0xbfb8aa3b, v52
	v_mul_f32_e32 v63, 0xbfb8aa3b, v53
	v_rcp_f32_e32 v60, v60
	v_rcp_f32_e32 v61, v61
	v_exp_f32_e32 v62, v62
	v_exp_f32_e32 v63, v63
	v_pk_mul_f32 v[54:55], v[54:55], v[58:59] op_sel_hi:[1,0]
	v_pk_mul_f32 v[50:51], v[50:51], v[60:61]
	v_add_f32_e32 v60, 1.0, v62
	v_add_f32_e32 v61, 1.0, v63
	v_rcp_f32_e32 v60, v60
	v_rcp_f32_e32 v61, v61
	v_pk_mul_f32 v[50:51], v[54:55], v[50:51]
	v_pk_mul_f32 v[54:55], v[56:57], v[58:59] op_sel_hi:[1,0]
	v_mul_f32_e32 v56, 0xbfb8aa3b, v43
	v_pk_mul_f32 v[52:53], v[52:53], v[60:61]
	v_exp_f32_e32 v56, v56
	v_pk_mul_f32 v[52:53], v[54:55], v[52:53]
	v_mul_f32_e32 v55, 0xbfb8aa3b, v42
	v_exp_f32_e32 v55, v55
	v_add_u32_e32 v54, 0xc6000, v123
	v_add_u32_e32 v132, v54, v141
	v_cvt_pk_bf16_f32 v50, v50, v51
	v_cvt_pk_bf16_f32 v51, v52, v53
	v_lshl_add_u64 v[52:53], v[132:133], 1, s[2:3]
	ds_write_b64 v164, v[50:51] offset:6144
	v_add_f32_e32 v50, 1.0, v55
	v_add_f32_e32 v51, 1.0, v56
	v_mul_f32_e32 v52, 0xbfb8aa3b, v44
	v_mul_f32_e32 v53, 0xbfb8aa3b, v45
	v_rcp_f32_e32 v50, v50
	v_rcp_f32_e32 v51, v51
	v_exp_f32_e32 v52, v52
	v_exp_f32_e32 v53, v53
	v_pk_mul_f32 v[34:35], v[34:35], v[58:59] op_sel_hi:[1,0]
	v_pk_mul_f32 v[42:43], v[42:43], v[50:51]
	v_add_f32_e32 v50, 1.0, v52
	v_add_f32_e32 v51, 1.0, v53
	v_rcp_f32_e32 v50, v50
	v_rcp_f32_e32 v51, v51
	v_pk_mul_f32 v[42:43], v[46:47], v[42:43]
	v_pk_mul_f32 v[46:47], v[48:49], v[134:135] op_sel_hi:[1,0]
	v_add_u32_e32 v132, v116, v59
	v_pk_mul_f32 v[44:45], v[44:45], v[50:51]
	v_cvt_pk_bf16_f32 v42, v42, v43
	v_pk_mul_f32 v[44:45], v[46:47], v[44:45]
	v_mul_f32_e32 v46, 0xbfb8aa3b, v34
	v_mul_f32_e32 v47, 0xbfb8aa3b, v35
	v_exp_f32_e32 v46, v46
	v_exp_f32_e32 v47, v47
	v_cvt_pk_bf16_f32 v43, v44, v45
	v_lshl_add_u64 v[44:45], v[132:133], 1, s[2:3]
	v_pk_mul_f32 v[36:37], v[36:37], v[58:59] op_sel_hi:[1,0]
	ds_write_b64 v165, v[42:43] offset:4096
	v_add_f32_e32 v42, 1.0, v46
	v_add_f32_e32 v43, 1.0, v47
	v_mul_f32_e32 v44, 0xbfb8aa3b, v36
	v_mul_f32_e32 v45, 0xbfb8aa3b, v37
	v_rcp_f32_e32 v42, v42
	v_rcp_f32_e32 v43, v43
	v_exp_f32_e32 v44, v44
	v_exp_f32_e32 v45, v45
	v_pk_mul_f32 v[38:39], v[38:39], v[58:59] op_sel_hi:[1,0]
	v_pk_mul_f32 v[34:35], v[34:35], v[42:43]
	v_add_f32_e32 v42, 1.0, v44
	v_add_f32_e32 v43, 1.0, v45
	v_rcp_f32_e32 v42, v42
	v_rcp_f32_e32 v43, v43
	v_pk_mul_f32 v[34:35], v[38:39], v[34:35]
	v_pk_mul_f32 v[38:39], v[40:41], v[58:59] op_sel_hi:[1,0]
	v_pk_mul_f32 v[26:27], v[26:27], v[134:135] op_sel_hi:[1,0]
	v_pk_mul_f32 v[36:37], v[36:37], v[42:43]
	v_add_u32_e32 v132, v116, v54
	v_pk_mul_f32 v[36:37], v[38:39], v[36:37]
	v_mul_f32_e32 v38, 0xbfb8aa3b, v26
	v_mul_f32_e32 v39, 0xbfb8aa3b, v27
	v_exp_f32_e32 v38, v38
	v_exp_f32_e32 v39, v39
	v_cvt_pk_bf16_f32 v34, v34, v35
	v_cvt_pk_bf16_f32 v35, v36, v37
	v_lshl_add_u64 v[36:37], v[132:133], 1, s[2:3]
	v_pk_mul_f32 v[28:29], v[28:29], v[134:135] op_sel_hi:[1,0]
	ds_write_b64 v165, v[34:35] offset:6144
	v_add_f32_e32 v34, 1.0, v38
	v_add_f32_e32 v35, 1.0, v39
; DEVI float silu(float x) { return x * __builtin_amdgcn_rcpf(1.f + __expf(-x)); }
; template <int EPI, int NRM>
; DEVI void epilogue(acc_t& acc, int pn, int trow, const EpiArgs& e, const float* rl, bf16* shmx) {
;     ...
;   } else if constexpr (EPI == EPI_SWIGLU) {
; #pragma unroll
;     for (int bj = 0; bj < 2; ++bj)
; #pragma unroll
;       for (int m = 0; m < 4; ++m)
; #pragma unroll
;         for (int n = 0; n < 2; ++n) {
;           float r[4];
; #pragma unroll
;           for (int j = 0; j < 4; ++j) r[j] = silu(acc[0][bj][m][n][j] * rs[bj][n]) * (acc[1][bj][m][n][j] * rs[bj][n]);
;           uint2 o; o.x = pack2(r[0], r[1]); o.y = pack2(r[2], r[3]);
;           const unsigned off = (unsigned)((tk0 + bj * 128 + n * 16) * DFF + pn * 128 + m * 16 + fl0);
;           *reinterpret_cast<uint2*>(e.o0 + off) = o;
;         }
	v_mul_f32_e32 v36, 0xbfb8aa3b, v28
	v_mul_f32_e32 v37, 0xbfb8aa3b, v29
	v_rcp_f32_e32 v34, v34
	v_rcp_f32_e32 v35, v35
	v_exp_f32_e32 v36, v36
	v_exp_f32_e32 v37, v37
	v_pk_mul_f32 v[30:31], v[30:31], v[134:135] op_sel_hi:[1,0]
	v_pk_mul_f32 v[26:27], v[26:27], v[34:35]
	v_add_f32_e32 v34, 1.0, v36
	v_add_f32_e32 v35, 1.0, v37
	v_rcp_f32_e32 v34, v34
	v_rcp_f32_e32 v35, v35
	v_pk_mul_f32 v[26:27], v[30:31], v[26:27]
	v_pk_mul_f32 v[30:31], v[32:33], v[134:135] op_sel_hi:[1,0]
	v_pk_mul_f32 v[18:19], v[18:19], v[58:59] op_sel_hi:[1,0]
	v_pk_mul_f32 v[28:29], v[28:29], v[34:35]
	v_add_u32_e32 v132, v100, v59
	v_pk_mul_f32 v[28:29], v[30:31], v[28:29]
	v_mul_f32_e32 v30, 0xbfb8aa3b, v18
	v_mul_f32_e32 v31, 0xbfb8aa3b, v19
	v_exp_f32_e32 v30, v30
	v_exp_f32_e32 v31, v31
	v_cvt_pk_bf16_f32 v26, v26, v27
	v_cvt_pk_bf16_f32 v27, v28, v29
	v_lshl_add_u64 v[28:29], v[132:133], 1, s[2:3]
	v_pk_mul_f32 v[20:21], v[20:21], v[58:59] op_sel_hi:[1,0]
	ds_write_b64 v166, v[26:27] offset:4096
	v_add_f32_e32 v26, 1.0, v30
	v_add_f32_e32 v27, 1.0, v31
	v_mul_f32_e32 v28, 0xbfb8aa3b, v20
	v_mul_f32_e32 v29, 0xbfb8aa3b, v21
	v_rcp_f32_e32 v26, v26
	v_rcp_f32_e32 v27, v27
	v_exp_f32_e32 v28, v28
	v_exp_f32_e32 v29, v29
	v_pk_mul_f32 v[22:23], v[22:23], v[58:59] op_sel_hi:[1,0]
	v_pk_mul_f32 v[18:19], v[18:19], v[26:27]
	v_add_f32_e32 v26, 1.0, v28
	v_add_f32_e32 v27, 1.0, v29
	v_rcp_f32_e32 v26, v26
	v_rcp_f32_e32 v27, v27
	v_pk_mul_f32 v[18:19], v[22:23], v[18:19]
	v_pk_mul_f32 v[22:23], v[24:25], v[58:59] op_sel_hi:[1,0]
	v_pk_mul_f32 v[10:11], v[10:11], v[134:135] op_sel_hi:[1,0]
	v_pk_mul_f32 v[20:21], v[20:21], v[26:27]
	v_add_u32_e32 v132, v100, v54
	v_pk_mul_f32 v[20:21], v[22:23], v[20:21]
	v_mul_f32_e32 v22, 0xbfb8aa3b, v10
	v_mul_f32_e32 v23, 0xbfb8aa3b, v11
	v_exp_f32_e32 v22, v22
	v_exp_f32_e32 v23, v23
	v_cvt_pk_bf16_f32 v18, v18, v19
	v_cvt_pk_bf16_f32 v19, v20, v21
	v_lshl_add_u64 v[20:21], v[132:133], 1, s[2:3]
	v_pk_mul_f32 v[12:13], v[12:13], v[134:135] op_sel_hi:[1,0]
	ds_write_b64 v166, v[18:19] offset:6144
	v_add_f32_e32 v18, 1.0, v22
	v_add_f32_e32 v19, 1.0, v23
	v_mul_f32_e32 v20, 0xbfb8aa3b, v12
	v_mul_f32_e32 v21, 0xbfb8aa3b, v13
	v_rcp_f32_e32 v18, v18
	v_rcp_f32_e32 v19, v19
	v_exp_f32_e32 v20, v20
	v_exp_f32_e32 v21, v21
	v_pk_mul_f32 v[14:15], v[14:15], v[134:135] op_sel_hi:[1,0]
	v_pk_mul_f32 v[10:11], v[10:11], v[18:19]
	v_add_f32_e32 v18, 1.0, v20
	v_add_f32_e32 v19, 1.0, v21
	v_rcp_f32_e32 v18, v18
	v_rcp_f32_e32 v19, v19
	v_pk_mul_f32 v[10:11], v[14:15], v[10:11]
	v_pk_mul_f32 v[14:15], v[16:17], v[134:135] op_sel_hi:[1,0]
	v_pk_mul_f32 v[2:3], v[2:3], v[58:59] op_sel_hi:[1,0]
	v_pk_mul_f32 v[12:13], v[12:13], v[18:19]
	v_add_u32_e32 v132, v84, v59
	v_pk_mul_f32 v[12:13], v[14:15], v[12:13]
	v_mul_f32_e32 v14, 0xbfb8aa3b, v2
	v_mul_f32_e32 v15, 0xbfb8aa3b, v3
	v_exp_f32_e32 v14, v14
	v_exp_f32_e32 v15, v15
	v_cvt_pk_bf16_f32 v10, v10, v11
	v_cvt_pk_bf16_f32 v11, v12, v13
	v_lshl_add_u64 v[12:13], v[132:133], 1, s[2:3]
	v_pk_mul_f32 v[4:5], v[4:5], v[58:59] op_sel_hi:[1,0]
	ds_write_b64 v167, v[10:11] offset:4096
	v_add_f32_e32 v10, 1.0, v14
	v_add_f32_e32 v11, 1.0, v15
	v_mul_f32_e32 v12, 0xbfb8aa3b, v4
	v_mul_f32_e32 v13, 0xbfb8aa3b, v5
	v_rcp_f32_e32 v10, v10
	v_rcp_f32_e32 v11, v11
	v_exp_f32_e32 v12, v12
	v_exp_f32_e32 v13, v13
	v_pk_mul_f32 v[6:7], v[6:7], v[58:59] op_sel_hi:[1,0]
	v_pk_mul_f32 v[2:3], v[2:3], v[10:11]
	v_add_f32_e32 v10, 1.0, v12
	v_add_f32_e32 v11, 1.0, v13
	v_rcp_f32_e32 v10, v10
	v_rcp_f32_e32 v11, v11
	v_pk_mul_f32 v[2:3], v[6:7], v[2:3]
	v_pk_mul_f32 v[6:7], v[8:9], v[58:59] op_sel_hi:[1,0]
	v_add_u32_e32 v132, v84, v54
	v_pk_mul_f32 v[4:5], v[4:5], v[10:11]
	v_cvt_pk_bf16_f32 v2, v2, v3
	v_pk_mul_f32 v[4:5], v[6:7], v[4:5]
	s_add_i32 s16, s16, 1
	v_cvt_pk_bf16_f32 v3, v4, v5
	v_lshl_add_u64 v[4:5], v[132:133], 1, s[2:3]
	s_andn2_b64 vcc, exec, s[4:5]
	s_mov_b32 s14, s8
	s_mov_b32 s12, s10
	ds_write_b64 v167, v[2:3] offset:6144
	s_waitcnt lgkmcnt(0)
	ds_read_b128 v[188:191], v168 offset:4096
	ds_read_b128 v[192:195], v168 offset:5120
	ds_read_b128 v[196:199], v168 offset:6144
	ds_read_b128 v[200:203], v168 offset:7168
	v_add_u32_e32 v207, 0x160000, v169
	v_add_u32_e32 v208, 0x176000, v169
	v_add_u32_e32 v209, 0x18c000, v169
	v_add_u32_e32 v210, 0x1a2000, v169
	s_waitcnt lgkmcnt(3)
	global_store_dwordx4 v207, v[188:191], s[2:3] nt
	s_waitcnt lgkmcnt(2)
	global_store_dwordx4 v208, v[192:195], s[2:3] nt
	s_waitcnt lgkmcnt(1)
	global_store_dwordx4 v209, v[196:199], s[2:3] nt
	s_waitcnt lgkmcnt(0)
	global_store_dwordx4 v210, v[200:203], s[2:3] nt
	s_cbranch_vccz .LBB0_2068
